# INA log-gate path in packed f32 math; INA full-grid phases start workgroup groups staggered (s_sleep) to spread epilogue store bursts
# speedup vs baseline: 1.0736x; 1.0059x over previous
.LBB0_793:
	s_and_b32 s8, s8, 3
	v_readlane_b32 s12, v240, 14
	s_lshr_b32 s43, s64, 6
	s_lshl_b32 s44, s9, 6
	s_lshl_b32 s10, s9, 13
	s_lshl_b32 s45, s8, 5
	s_lshl_b32 s11, s8, 12
	s_mulk_i32 s12, 0xc00
	v_readlane_b32 s16, v242, 5
	v_readlane_b32 s17, v242, 6
	s_add_u32 s16, s16, s12
	s_addc_u32 s17, s17, 0
	s_add_i32 m0, s35, 0x18000
	v_lshl_add_u64 v[12:13], v[12:13], 0, s[6:7]
	s_waitcnt vmcnt(4)
	s_barrier
	global_load_lds_dwordx4 v[12:13], off
	v_lshl_add_u64 v[10:11], v[10:11], 0, s[6:7]
	s_add_i32 m0, s35, 0x1a000
	s_add_i32 s46, s35, 0x8000
	global_load_lds_dwordx4 v[10:11], off
	v_lshl_add_u64 v[8:9], v[8:9], 0, s[6:7]
	s_mov_b32 m0, s46
	s_add_i32 s47, s35, 0xa000
	global_load_lds_dwordx4 v[8:9], off
	v_lshl_add_u64 v[6:7], v[6:7], 0, s[6:7]
	s_mov_b32 m0, s47
	v_lshl_add_u64 v[4:5], v[4:5], 0, s[6:7]
	global_load_lds_dwordx4 v[6:7], off
	s_add_i32 m0, s35, 0x1c000
	v_lshl_add_u64 v[2:3], v[2:3], 0, s[6:7]
	global_load_lds_dwordx4 v[4:5], off
	s_add_i32 m0, s35, 0x1e000
	v_bfe_u32 v1, v14, 4, 2
	global_load_lds_dwordx4 v[2:3], off
	v_and_b32_e32 v170, 15, v14
	v_lshlrev_b32_e32 v2, 4, v1
	v_lshlrev_b32_e32 v3, 2, v14
	v_lshl_or_b32 v2, v170, 6, v2
	v_and_b32_e32 v3, 32, v3
	s_lshl_b32 s63, s57, 3
	v_bitop3_b32 v4, v2, s10, v3 bitop3:0xde
	v_bitop3_b32 v171, v2, s11, v3 bitop3:0xde
	v_cvt_f32_u32_e32 v2, s63
	s_lshl_b32 s9, s9, 11
	s_lshl_b32 s10, s8, 9
	s_add_i32 s9, s9, 0
	v_rcp_iflag_f32_e32 v2, v2
	s_lshr_b32 s49, s38, 3
	s_add_i32 s66, s9, s10
	s_add_i32 s48, s43, -2
	v_mul_f32_e32 v2, 0x4f7ffffe, v2
	v_cvt_u32_f32_e32 v2, v2
	s_and_b32 s64, s38, 7
	s_add_i32 s65, s49, 1
	s_add_i32 s66, s66, 0x20000
	s_lshl_b32 s8, s8, 7
	v_readlane_b32 s10, v243, 29
	v_readlane_b32 s11, v243, 30
	s_add_u32 s18, s10, s8
	s_addc_u32 s19, s11, 0
	v_readlane_b32 s10, v243, 4
	v_readlane_b32 s11, v243, 5
	s_add_u32 s20, s10, s8
	v_readfirstlane_b32 s9, v2
	v_add_u32_e32 v2, v17, v15
	s_addc_u32 s21, s11, 0
	s_sub_i32 s8, 0, s63
	v_add_lshl_u32 v2, v2, v16, 1
	v_mov_b32_e32 v3, v0
	s_waitcnt vmcnt(6)
	s_mul_i32 s8, s8, s9
	v_lshl_add_u64 v[138:139], s[92:93], 0, v[2:3]
	v_add_u32_e32 v2, v20, v18
	s_mul_hi_u32 s8, s9, s8
	v_add_lshl_u32 v2, v2, v19, 1
	s_mov_b32 s39, s93
	s_mov_b32 s67, 0
	s_add_i32 s68, s9, s8
	v_lshl_add_u64 v[140:141], s[92:93], 0, v[2:3]
	s_mov_b32 s26, -1
	v_add_u32_e32 v172, 0, v4
	s_barrier
	v_readlane_b32 s98, v240, 13
	v_readlane_b32 s99, v241, 25
	s_nop 3
	s_bfe_u32 s98, s98, 0x20003
	s_cmp_lg_u32 s98, 0
	s_cbranch_scc1 .Lstag_795_done
	s_bfe_u32 s98, s99, 0x20003
	s_cmp_eq_u32 s98, 0
	s_cbranch_scc1 .Lstag_795_done
.Lstag_795_loop:
	s_sleep 16
	s_sub_i32 s98, s98, 1
	s_cmp_lg_u32 s98, 0
	s_cbranch_scc1 .Lstag_795_loop
.Lstag_795_done:
	s_branch .LBB0_795
.LBB0_794:
	s_and_b64 vcc, exec, s[8:9]
	s_mov_b32 s71, s70
	s_mov_b32 s26, s69
	s_mov_b64 s[4:5], s[24:25]
	s_mov_b64 s[0:1], s[22:23]
	s_cbranch_vccnz .LBB0_971

.LBB0_822:
	s_mov_b64 s[0:1], -1
	s_and_b64 vcc, exec, s[28:29]
	s_cbranch_vccz .LBB0_824
	s_mov_b32 s0, 0x3fb8aa3b
	s_mov_b32 s4, 0x3f317217
	s_mov_b32 s10, 0x3377d1cf
	v_lshl_add_u64 v[176:177], v[168:169], 2, s[86:87]
	v_pk_mul_f32 v[114:115], v[166:167], s[0:1] op_sel_hi:[1,0]
	v_pk_mul_f32 v[116:117], v[164:165], s[0:1] op_sel_hi:[1,0]
	v_pk_mul_f32 v[118:119], v[162:163], s[0:1] op_sel_hi:[1,0]
	v_pk_mul_f32 v[120:121], v[160:161], s[0:1] op_sel_hi:[1,0]
	v_exp_f32_e32 v114, v114
	v_exp_f32_e32 v115, v115
	v_exp_f32_e32 v116, v116
	v_exp_f32_e32 v117, v117
	v_exp_f32_e32 v118, v118
	v_exp_f32_e32 v119, v119
	v_exp_f32_e32 v120, v120
	v_exp_f32_e32 v121, v121
	v_pk_add_f32 v[114:115], v[114:115], 1.0 op_sel_hi:[1,0]
	v_pk_add_f32 v[116:117], v[116:117], 1.0 op_sel_hi:[1,0]
	v_pk_add_f32 v[118:119], v[118:119], 1.0 op_sel_hi:[1,0]
	v_pk_add_f32 v[120:121], v[120:121], 1.0 op_sel_hi:[1,0]
	v_rcp_f32_e32 v114, v114
	v_rcp_f32_e32 v115, v115
	v_rcp_f32_e32 v116, v116
	v_rcp_f32_e32 v117, v117
	v_rcp_f32_e32 v118, v118
	v_rcp_f32_e32 v119, v119
	v_rcp_f32_e32 v120, v120
	v_rcp_f32_e32 v121, v121
	s_waitcnt vmcnt(0)
	v_pk_mul_f32 v[114:115], v[114:115], v[220:221]
	v_pk_mul_f32 v[116:117], v[116:117], v[222:223]
	v_pk_mul_f32 v[118:119], v[118:119], v[224:225]
	v_pk_mul_f32 v[120:121], v[120:121], v[226:227]
	v_min_f32_e32 v114, 0x3f7fffef, v114
	v_min_f32_e32 v115, 0x3f7fffef, v115
	v_min_f32_e32 v116, 0x3f7fffef, v116
	v_min_f32_e32 v117, 0x3f7fffef, v117
	v_min_f32_e32 v118, 0x3f7fffef, v118
	v_min_f32_e32 v119, 0x3f7fffef, v119
	v_min_f32_e32 v120, 0x3f7fffef, v120
	v_min_f32_e32 v121, 0x3f7fffef, v121
	v_pk_add_f32 v[114:115], v[114:115], 1.0 op_sel_hi:[1,0] neg_lo:[1,0] neg_hi:[1,0]
	v_pk_add_f32 v[116:117], v[116:117], 1.0 op_sel_hi:[1,0] neg_lo:[1,0] neg_hi:[1,0]
	v_pk_add_f32 v[118:119], v[118:119], 1.0 op_sel_hi:[1,0] neg_lo:[1,0] neg_hi:[1,0]
	v_pk_add_f32 v[120:121], v[120:121], 1.0 op_sel_hi:[1,0] neg_lo:[1,0] neg_hi:[1,0]
	v_log_f32_e32 v114, v114
	v_log_f32_e32 v115, v115
	v_log_f32_e32 v116, v116
	v_log_f32_e32 v117, v117
	v_log_f32_e32 v118, v118
	v_log_f32_e32 v119, v119
	v_log_f32_e32 v120, v120
	v_log_f32_e32 v121, v121
	v_pk_mul_f32 v[244:245], v[114:115], s[4:5] op_sel_hi:[1,0]
	v_pk_fma_f32 v[244:245], v[114:115], s[4:5], v[244:245] op_sel_hi:[1,0,1] neg_lo:[0,0,1] neg_hi:[0,0,1]
	v_pk_fma_f32 v[244:245], v[114:115], s[10:11], v[244:245] op_sel_hi:[1,0,1]
	v_pk_fma_f32 v[114:115], v[114:115], s[4:5], v[244:245] op_sel_hi:[1,0,1]
	v_pk_mul_f32 v[246:247], v[116:117], s[4:5] op_sel_hi:[1,0]
	v_pk_fma_f32 v[246:247], v[116:117], s[4:5], v[246:247] op_sel_hi:[1,0,1] neg_lo:[0,0,1] neg_hi:[0,0,1]
	v_pk_fma_f32 v[246:247], v[116:117], s[10:11], v[246:247] op_sel_hi:[1,0,1]
	v_pk_fma_f32 v[116:117], v[116:117], s[4:5], v[246:247] op_sel_hi:[1,0,1]
	v_pk_mul_f32 v[244:245], v[118:119], s[4:5] op_sel_hi:[1,0]
	v_pk_fma_f32 v[244:245], v[118:119], s[4:5], v[244:245] op_sel_hi:[1,0,1] neg_lo:[0,0,1] neg_hi:[0,0,1]
	v_pk_fma_f32 v[244:245], v[118:119], s[10:11], v[244:245] op_sel_hi:[1,0,1]
	v_pk_fma_f32 v[118:119], v[118:119], s[4:5], v[244:245] op_sel_hi:[1,0,1]
	v_pk_mul_f32 v[246:247], v[120:121], s[4:5] op_sel_hi:[1,0]
	v_pk_fma_f32 v[246:247], v[120:121], s[4:5], v[246:247] op_sel_hi:[1,0,1] neg_lo:[0,0,1] neg_hi:[0,0,1]
	v_pk_fma_f32 v[246:247], v[120:121], s[10:11], v[246:247] op_sel_hi:[1,0,1]
	v_pk_fma_f32 v[120:121], v[120:121], s[4:5], v[246:247] op_sel_hi:[1,0,1]
	s_mov_b64 s[0:1], 0
	global_store_dwordx4 v[176:177], v[114:117], off
	global_store_dwordx4 v[176:177], v[118:121], off offset:16

.LBB0_835:
	s_andn2_b64 vcc, exec, s[0:1]
	s_cbranch_vccnz .LBB0_852
	v_mad_i64_i32 v[150:151], s[0:1], v114, s33, v[122:123]
	s_cmp_gt_i32 s71, 8
	s_mov_b64 s[0:1], -1
	s_cbranch_scc1 .LBB0_842
	s_cmp_lt_u32 s73, 5
	s_cselect_b64 s[0:1], -1, 0
	s_cmp_gt_u32 s73, 4
	s_cbranch_scc0 .LBB0_842
	s_andn2_b64 vcc, exec, s[28:29]
	s_mov_b64 s[4:5], -1
	s_cbranch_vccnz .LBB0_840
	s_mov_b32 s4, 0x3fb8aa3b
	s_mov_b32 s76, 0x3f317217
	s_mov_b32 s12, 0x3377d1cf
	v_lshl_add_u64 v[152:153], v[150:151], 2, s[86:87]
	v_pk_mul_f32 v[98:99], v[148:149], s[4:5] op_sel_hi:[1,0]
	v_pk_mul_f32 v[100:101], v[120:121], s[4:5] op_sel_hi:[1,0]
	v_pk_mul_f32 v[102:103], v[118:119], s[4:5] op_sel_hi:[1,0]
	v_pk_mul_f32 v[104:105], v[116:117], s[4:5] op_sel_hi:[1,0]
	v_exp_f32_e32 v98, v98
	v_exp_f32_e32 v99, v99
	v_exp_f32_e32 v100, v100
	v_exp_f32_e32 v101, v101
	v_exp_f32_e32 v102, v102
	v_exp_f32_e32 v103, v103
	v_exp_f32_e32 v104, v104
	v_exp_f32_e32 v105, v105
	v_pk_add_f32 v[98:99], v[98:99], 1.0 op_sel_hi:[1,0]
	v_pk_add_f32 v[100:101], v[100:101], 1.0 op_sel_hi:[1,0]
	v_pk_add_f32 v[102:103], v[102:103], 1.0 op_sel_hi:[1,0]
	v_pk_add_f32 v[104:105], v[104:105], 1.0 op_sel_hi:[1,0]
	v_rcp_f32_e32 v98, v98
	v_rcp_f32_e32 v99, v99
	v_rcp_f32_e32 v100, v100
	v_rcp_f32_e32 v101, v101
	v_rcp_f32_e32 v102, v102
	v_rcp_f32_e32 v103, v103
	v_rcp_f32_e32 v104, v104
	v_rcp_f32_e32 v105, v105
	v_pk_mul_f32 v[98:99], v[98:99], v[220:221]
	v_pk_mul_f32 v[100:101], v[100:101], v[222:223]
	v_pk_mul_f32 v[102:103], v[102:103], v[224:225]
	v_pk_mul_f32 v[104:105], v[104:105], v[226:227]
	v_min_f32_e32 v98, 0x3f7fffef, v98
	v_min_f32_e32 v99, 0x3f7fffef, v99
	v_min_f32_e32 v100, 0x3f7fffef, v100
	v_min_f32_e32 v101, 0x3f7fffef, v101
	v_min_f32_e32 v102, 0x3f7fffef, v102
	v_min_f32_e32 v103, 0x3f7fffef, v103
	v_min_f32_e32 v104, 0x3f7fffef, v104
	v_min_f32_e32 v105, 0x3f7fffef, v105
	v_pk_add_f32 v[98:99], v[98:99], 1.0 op_sel_hi:[1,0] neg_lo:[1,0] neg_hi:[1,0]
	v_pk_add_f32 v[100:101], v[100:101], 1.0 op_sel_hi:[1,0] neg_lo:[1,0] neg_hi:[1,0]
	v_pk_add_f32 v[102:103], v[102:103], 1.0 op_sel_hi:[1,0] neg_lo:[1,0] neg_hi:[1,0]
	v_pk_add_f32 v[104:105], v[104:105], 1.0 op_sel_hi:[1,0] neg_lo:[1,0] neg_hi:[1,0]
	v_log_f32_e32 v98, v98
	v_log_f32_e32 v99, v99
	v_log_f32_e32 v100, v100
	v_log_f32_e32 v101, v101
	v_log_f32_e32 v102, v102
	v_log_f32_e32 v103, v103
	v_log_f32_e32 v104, v104
	v_log_f32_e32 v105, v105
	v_pk_mul_f32 v[244:245], v[98:99], s[76:77] op_sel_hi:[1,0]
	v_pk_fma_f32 v[244:245], v[98:99], s[76:77], v[244:245] op_sel_hi:[1,0,1] neg_lo:[0,0,1] neg_hi:[0,0,1]
	v_pk_fma_f32 v[244:245], v[98:99], s[12:13], v[244:245] op_sel_hi:[1,0,1]
	v_pk_fma_f32 v[98:99], v[98:99], s[76:77], v[244:245] op_sel_hi:[1,0,1]
	v_pk_mul_f32 v[246:247], v[100:101], s[76:77] op_sel_hi:[1,0]
	v_pk_fma_f32 v[246:247], v[100:101], s[76:77], v[246:247] op_sel_hi:[1,0,1] neg_lo:[0,0,1] neg_hi:[0,0,1]
	v_pk_fma_f32 v[246:247], v[100:101], s[12:13], v[246:247] op_sel_hi:[1,0,1]
	v_pk_fma_f32 v[100:101], v[100:101], s[76:77], v[246:247] op_sel_hi:[1,0,1]
	v_pk_mul_f32 v[244:245], v[102:103], s[76:77] op_sel_hi:[1,0]
	v_pk_fma_f32 v[244:245], v[102:103], s[76:77], v[244:245] op_sel_hi:[1,0,1] neg_lo:[0,0,1] neg_hi:[0,0,1]
	v_pk_fma_f32 v[244:245], v[102:103], s[12:13], v[244:245] op_sel_hi:[1,0,1]
	v_pk_fma_f32 v[102:103], v[102:103], s[76:77], v[244:245] op_sel_hi:[1,0,1]
	v_pk_mul_f32 v[246:247], v[104:105], s[76:77] op_sel_hi:[1,0]
	v_pk_fma_f32 v[246:247], v[104:105], s[76:77], v[246:247] op_sel_hi:[1,0,1] neg_lo:[0,0,1] neg_hi:[0,0,1]
	v_pk_fma_f32 v[246:247], v[104:105], s[12:13], v[246:247] op_sel_hi:[1,0,1]
	v_pk_fma_f32 v[104:105], v[104:105], s[76:77], v[246:247] op_sel_hi:[1,0,1]
	s_mov_b64 s[4:5], 0
	global_store_dwordx4 v[152:153], v[98:101], off
	global_store_dwordx4 v[152:153], v[102:105], off offset:16

.LBB0_844:
	s_nop 1
	v_mad_i64_i32 v[98:99], s[0:1], v114, s33, 0
	v_lshl_add_u64 v[114:115], v[98:99], 0, v[124:125]
	s_cmp_gt_i32 s71, 8
	s_mov_b64 s[0:1], -1
	s_cbranch_scc1 .LBB0_850
	s_cmp_lt_u32 s73, 5
	s_cselect_b64 s[0:1], -1, 0
	s_cmp_gt_u32 s73, 4
	s_cbranch_scc0 .LBB0_850
	s_andn2_b64 vcc, exec, s[28:29]
	s_mov_b64 s[4:5], -1
	s_cbranch_vccnz .LBB0_848
	s_mov_b32 s4, 0x3fb8aa3b
	s_mov_b32 s76, 0x3f317217
	s_mov_b32 s12, 0x3377d1cf
	v_lshl_add_u64 v[116:117], v[114:115], 2, s[86:87]
	v_pk_mul_f32 v[98:99], v[112:113], s[4:5] op_sel_hi:[1,0]
	v_pk_mul_f32 v[100:101], v[110:111], s[4:5] op_sel_hi:[1,0]
	v_pk_mul_f32 v[102:103], v[108:109], s[4:5] op_sel_hi:[1,0]
	v_pk_mul_f32 v[104:105], v[106:107], s[4:5] op_sel_hi:[1,0]
	v_exp_f32_e32 v98, v98
	v_exp_f32_e32 v99, v99
	v_exp_f32_e32 v100, v100
	v_exp_f32_e32 v101, v101
	v_exp_f32_e32 v102, v102
	v_exp_f32_e32 v103, v103
	v_exp_f32_e32 v104, v104
	v_exp_f32_e32 v105, v105
	v_pk_add_f32 v[98:99], v[98:99], 1.0 op_sel_hi:[1,0]
	v_pk_add_f32 v[100:101], v[100:101], 1.0 op_sel_hi:[1,0]
	v_pk_add_f32 v[102:103], v[102:103], 1.0 op_sel_hi:[1,0]
	v_pk_add_f32 v[104:105], v[104:105], 1.0 op_sel_hi:[1,0]
	v_rcp_f32_e32 v98, v98
	v_rcp_f32_e32 v99, v99
	v_rcp_f32_e32 v100, v100
	v_rcp_f32_e32 v101, v101
	v_rcp_f32_e32 v102, v102
	v_rcp_f32_e32 v103, v103
	v_rcp_f32_e32 v104, v104
	v_rcp_f32_e32 v105, v105
	v_pk_mul_f32 v[98:99], v[98:99], v[228:229]
	v_pk_mul_f32 v[100:101], v[100:101], v[230:231]
	v_pk_mul_f32 v[102:103], v[102:103], v[232:233]
	v_pk_mul_f32 v[104:105], v[104:105], v[234:235]
	v_min_f32_e32 v98, 0x3f7fffef, v98
	v_min_f32_e32 v99, 0x3f7fffef, v99
	v_min_f32_e32 v100, 0x3f7fffef, v100
	v_min_f32_e32 v101, 0x3f7fffef, v101
	v_min_f32_e32 v102, 0x3f7fffef, v102
	v_min_f32_e32 v103, 0x3f7fffef, v103
	v_min_f32_e32 v104, 0x3f7fffef, v104
	v_min_f32_e32 v105, 0x3f7fffef, v105
	v_pk_add_f32 v[98:99], v[98:99], 1.0 op_sel_hi:[1,0] neg_lo:[1,0] neg_hi:[1,0]
	v_pk_add_f32 v[100:101], v[100:101], 1.0 op_sel_hi:[1,0] neg_lo:[1,0] neg_hi:[1,0]
	v_pk_add_f32 v[102:103], v[102:103], 1.0 op_sel_hi:[1,0] neg_lo:[1,0] neg_hi:[1,0]
	v_pk_add_f32 v[104:105], v[104:105], 1.0 op_sel_hi:[1,0] neg_lo:[1,0] neg_hi:[1,0]
	v_log_f32_e32 v98, v98
	v_log_f32_e32 v99, v99
	v_log_f32_e32 v100, v100
	v_log_f32_e32 v101, v101
	v_log_f32_e32 v102, v102
	v_log_f32_e32 v103, v103
	v_log_f32_e32 v104, v104
	v_log_f32_e32 v105, v105
	v_pk_mul_f32 v[244:245], v[98:99], s[76:77] op_sel_hi:[1,0]
	v_pk_fma_f32 v[244:245], v[98:99], s[76:77], v[244:245] op_sel_hi:[1,0,1] neg_lo:[0,0,1] neg_hi:[0,0,1]
	v_pk_fma_f32 v[244:245], v[98:99], s[12:13], v[244:245] op_sel_hi:[1,0,1]
	v_pk_fma_f32 v[98:99], v[98:99], s[76:77], v[244:245] op_sel_hi:[1,0,1]
	v_pk_mul_f32 v[246:247], v[100:101], s[76:77] op_sel_hi:[1,0]
	v_pk_fma_f32 v[246:247], v[100:101], s[76:77], v[246:247] op_sel_hi:[1,0,1] neg_lo:[0,0,1] neg_hi:[0,0,1]
	v_pk_fma_f32 v[246:247], v[100:101], s[12:13], v[246:247] op_sel_hi:[1,0,1]
	v_pk_fma_f32 v[100:101], v[100:101], s[76:77], v[246:247] op_sel_hi:[1,0,1]
	v_pk_mul_f32 v[244:245], v[102:103], s[76:77] op_sel_hi:[1,0]
	v_pk_fma_f32 v[244:245], v[102:103], s[76:77], v[244:245] op_sel_hi:[1,0,1] neg_lo:[0,0,1] neg_hi:[0,0,1]
	v_pk_fma_f32 v[244:245], v[102:103], s[12:13], v[244:245] op_sel_hi:[1,0,1]
	v_pk_fma_f32 v[102:103], v[102:103], s[76:77], v[244:245] op_sel_hi:[1,0,1]
	v_pk_mul_f32 v[246:247], v[104:105], s[76:77] op_sel_hi:[1,0]
	v_pk_fma_f32 v[246:247], v[104:105], s[76:77], v[246:247] op_sel_hi:[1,0,1] neg_lo:[0,0,1] neg_hi:[0,0,1]
	v_pk_fma_f32 v[246:247], v[104:105], s[12:13], v[246:247] op_sel_hi:[1,0,1]
	v_pk_fma_f32 v[104:105], v[104:105], s[76:77], v[246:247] op_sel_hi:[1,0,1]
	s_mov_b64 s[4:5], 0
	global_store_dwordx4 v[116:117], v[98:101], off
	global_store_dwordx4 v[116:117], v[102:105], off offset:16

.LBB0_854:
	s_andn2_b64 vcc, exec, s[0:1]
	s_cbranch_vccnz .LBB0_871
	v_mad_i64_i32 v[108:109], s[0:1], v98, s33, v[122:123]
	s_cmp_gt_i32 s71, 8
	s_mov_b64 s[0:1], -1
	s_cbranch_scc1 .LBB0_861
	s_cmp_lt_u32 s73, 5
	s_cselect_b64 s[0:1], -1, 0
	s_cmp_gt_u32 s73, 4
	s_cbranch_scc0 .LBB0_861
	s_andn2_b64 vcc, exec, s[28:29]
	s_mov_b64 s[4:5], -1
	s_cbranch_vccnz .LBB0_859
	s_mov_b32 s4, 0x3fb8aa3b
	s_mov_b32 s76, 0x3f317217
	s_mov_b32 s12, 0x3377d1cf
	v_lshl_add_u64 v[110:111], v[108:109], 2, s[86:87]
	v_pk_mul_f32 v[82:83], v[106:107], s[4:5] op_sel_hi:[1,0]
	v_pk_mul_f32 v[84:85], v[104:105], s[4:5] op_sel_hi:[1,0]
	v_pk_mul_f32 v[86:87], v[102:103], s[4:5] op_sel_hi:[1,0]
	v_pk_mul_f32 v[88:89], v[100:101], s[4:5] op_sel_hi:[1,0]
	v_exp_f32_e32 v82, v82
	v_exp_f32_e32 v83, v83
	v_exp_f32_e32 v84, v84
	v_exp_f32_e32 v85, v85
	v_exp_f32_e32 v86, v86
	v_exp_f32_e32 v87, v87
	v_exp_f32_e32 v88, v88
	v_exp_f32_e32 v89, v89
	v_pk_add_f32 v[82:83], v[82:83], 1.0 op_sel_hi:[1,0]
	v_pk_add_f32 v[84:85], v[84:85], 1.0 op_sel_hi:[1,0]
	v_pk_add_f32 v[86:87], v[86:87], 1.0 op_sel_hi:[1,0]
	v_pk_add_f32 v[88:89], v[88:89], 1.0 op_sel_hi:[1,0]
	v_rcp_f32_e32 v82, v82
	v_rcp_f32_e32 v83, v83
	v_rcp_f32_e32 v84, v84
	v_rcp_f32_e32 v85, v85
	v_rcp_f32_e32 v86, v86
	v_rcp_f32_e32 v87, v87
	v_rcp_f32_e32 v88, v88
	v_rcp_f32_e32 v89, v89
	v_pk_mul_f32 v[82:83], v[82:83], v[220:221]
	v_pk_mul_f32 v[84:85], v[84:85], v[222:223]
	v_pk_mul_f32 v[86:87], v[86:87], v[224:225]
	v_pk_mul_f32 v[88:89], v[88:89], v[226:227]
	v_min_f32_e32 v82, 0x3f7fffef, v82
	v_min_f32_e32 v83, 0x3f7fffef, v83
	v_min_f32_e32 v84, 0x3f7fffef, v84
	v_min_f32_e32 v85, 0x3f7fffef, v85
	v_min_f32_e32 v86, 0x3f7fffef, v86
	v_min_f32_e32 v87, 0x3f7fffef, v87
	v_min_f32_e32 v88, 0x3f7fffef, v88
	v_min_f32_e32 v89, 0x3f7fffef, v89
	v_pk_add_f32 v[82:83], v[82:83], 1.0 op_sel_hi:[1,0] neg_lo:[1,0] neg_hi:[1,0]
	v_pk_add_f32 v[84:85], v[84:85], 1.0 op_sel_hi:[1,0] neg_lo:[1,0] neg_hi:[1,0]
	v_pk_add_f32 v[86:87], v[86:87], 1.0 op_sel_hi:[1,0] neg_lo:[1,0] neg_hi:[1,0]
	v_pk_add_f32 v[88:89], v[88:89], 1.0 op_sel_hi:[1,0] neg_lo:[1,0] neg_hi:[1,0]
	v_log_f32_e32 v82, v82
	v_log_f32_e32 v83, v83
	v_log_f32_e32 v84, v84
	v_log_f32_e32 v85, v85
	v_log_f32_e32 v86, v86
	v_log_f32_e32 v87, v87
	v_log_f32_e32 v88, v88
	v_log_f32_e32 v89, v89
	v_pk_mul_f32 v[244:245], v[82:83], s[76:77] op_sel_hi:[1,0]
	v_pk_fma_f32 v[244:245], v[82:83], s[76:77], v[244:245] op_sel_hi:[1,0,1] neg_lo:[0,0,1] neg_hi:[0,0,1]
	v_pk_fma_f32 v[244:245], v[82:83], s[12:13], v[244:245] op_sel_hi:[1,0,1]
	v_pk_fma_f32 v[82:83], v[82:83], s[76:77], v[244:245] op_sel_hi:[1,0,1]
	v_pk_mul_f32 v[246:247], v[84:85], s[76:77] op_sel_hi:[1,0]
	v_pk_fma_f32 v[246:247], v[84:85], s[76:77], v[246:247] op_sel_hi:[1,0,1] neg_lo:[0,0,1] neg_hi:[0,0,1]
	v_pk_fma_f32 v[246:247], v[84:85], s[12:13], v[246:247] op_sel_hi:[1,0,1]
	v_pk_fma_f32 v[84:85], v[84:85], s[76:77], v[246:247] op_sel_hi:[1,0,1]
	v_pk_mul_f32 v[244:245], v[86:87], s[76:77] op_sel_hi:[1,0]
	v_pk_fma_f32 v[244:245], v[86:87], s[76:77], v[244:245] op_sel_hi:[1,0,1] neg_lo:[0,0,1] neg_hi:[0,0,1]
	v_pk_fma_f32 v[244:245], v[86:87], s[12:13], v[244:245] op_sel_hi:[1,0,1]
	v_pk_fma_f32 v[86:87], v[86:87], s[76:77], v[244:245] op_sel_hi:[1,0,1]
	v_pk_mul_f32 v[246:247], v[88:89], s[76:77] op_sel_hi:[1,0]
	v_pk_fma_f32 v[246:247], v[88:89], s[76:77], v[246:247] op_sel_hi:[1,0,1] neg_lo:[0,0,1] neg_hi:[0,0,1]
	v_pk_fma_f32 v[246:247], v[88:89], s[12:13], v[246:247] op_sel_hi:[1,0,1]
	v_pk_fma_f32 v[88:89], v[88:89], s[76:77], v[246:247] op_sel_hi:[1,0,1]
	s_mov_b64 s[4:5], 0
	global_store_dwordx4 v[110:111], v[82:85], off
	global_store_dwordx4 v[110:111], v[86:89], off offset:16

.LBB0_863:
	s_nop 1
	v_mad_i64_i32 v[82:83], s[0:1], v98, s33, 0
	v_lshl_add_u64 v[98:99], v[82:83], 0, v[124:125]
	s_cmp_gt_i32 s71, 8
	s_mov_b64 s[0:1], -1
	s_cbranch_scc1 .LBB0_869
	s_cmp_lt_u32 s73, 5
	s_cselect_b64 s[0:1], -1, 0
	s_cmp_gt_u32 s73, 4
	s_cbranch_scc0 .LBB0_869
	s_andn2_b64 vcc, exec, s[28:29]
	s_mov_b64 s[4:5], -1
	s_cbranch_vccnz .LBB0_867
	s_mov_b32 s4, 0x3fb8aa3b
	s_mov_b32 s76, 0x3f317217
	s_mov_b32 s12, 0x3377d1cf
	v_lshl_add_u64 v[100:101], v[98:99], 2, s[86:87]
	v_pk_mul_f32 v[82:83], v[96:97], s[4:5] op_sel_hi:[1,0]
	v_pk_mul_f32 v[84:85], v[94:95], s[4:5] op_sel_hi:[1,0]
	v_pk_mul_f32 v[86:87], v[92:93], s[4:5] op_sel_hi:[1,0]
	v_pk_mul_f32 v[88:89], v[90:91], s[4:5] op_sel_hi:[1,0]
	v_exp_f32_e32 v82, v82
	v_exp_f32_e32 v83, v83
	v_exp_f32_e32 v84, v84
	v_exp_f32_e32 v85, v85
	v_exp_f32_e32 v86, v86
	v_exp_f32_e32 v87, v87
	v_exp_f32_e32 v88, v88
	v_exp_f32_e32 v89, v89
	v_pk_add_f32 v[82:83], v[82:83], 1.0 op_sel_hi:[1,0]
	v_pk_add_f32 v[84:85], v[84:85], 1.0 op_sel_hi:[1,0]
	v_pk_add_f32 v[86:87], v[86:87], 1.0 op_sel_hi:[1,0]
	v_pk_add_f32 v[88:89], v[88:89], 1.0 op_sel_hi:[1,0]
	v_rcp_f32_e32 v82, v82
	v_rcp_f32_e32 v83, v83
	v_rcp_f32_e32 v84, v84
	v_rcp_f32_e32 v85, v85
	v_rcp_f32_e32 v86, v86
	v_rcp_f32_e32 v87, v87
	v_rcp_f32_e32 v88, v88
	v_rcp_f32_e32 v89, v89
	v_pk_mul_f32 v[82:83], v[82:83], v[228:229]
	v_pk_mul_f32 v[84:85], v[84:85], v[230:231]
	v_pk_mul_f32 v[86:87], v[86:87], v[232:233]
	v_pk_mul_f32 v[88:89], v[88:89], v[234:235]
	v_min_f32_e32 v82, 0x3f7fffef, v82
	v_min_f32_e32 v83, 0x3f7fffef, v83
	v_min_f32_e32 v84, 0x3f7fffef, v84
	v_min_f32_e32 v85, 0x3f7fffef, v85
	v_min_f32_e32 v86, 0x3f7fffef, v86
	v_min_f32_e32 v87, 0x3f7fffef, v87
	v_min_f32_e32 v88, 0x3f7fffef, v88
	v_min_f32_e32 v89, 0x3f7fffef, v89
	v_pk_add_f32 v[82:83], v[82:83], 1.0 op_sel_hi:[1,0] neg_lo:[1,0] neg_hi:[1,0]
	v_pk_add_f32 v[84:85], v[84:85], 1.0 op_sel_hi:[1,0] neg_lo:[1,0] neg_hi:[1,0]
	v_pk_add_f32 v[86:87], v[86:87], 1.0 op_sel_hi:[1,0] neg_lo:[1,0] neg_hi:[1,0]
	v_pk_add_f32 v[88:89], v[88:89], 1.0 op_sel_hi:[1,0] neg_lo:[1,0] neg_hi:[1,0]
	v_log_f32_e32 v82, v82
	v_log_f32_e32 v83, v83
	v_log_f32_e32 v84, v84
	v_log_f32_e32 v85, v85
	v_log_f32_e32 v86, v86
	v_log_f32_e32 v87, v87
	v_log_f32_e32 v88, v88
	v_log_f32_e32 v89, v89
	v_pk_mul_f32 v[244:245], v[82:83], s[76:77] op_sel_hi:[1,0]
	v_pk_fma_f32 v[244:245], v[82:83], s[76:77], v[244:245] op_sel_hi:[1,0,1] neg_lo:[0,0,1] neg_hi:[0,0,1]
	v_pk_fma_f32 v[244:245], v[82:83], s[12:13], v[244:245] op_sel_hi:[1,0,1]
	v_pk_fma_f32 v[82:83], v[82:83], s[76:77], v[244:245] op_sel_hi:[1,0,1]
	v_pk_mul_f32 v[246:247], v[84:85], s[76:77] op_sel_hi:[1,0]
	v_pk_fma_f32 v[246:247], v[84:85], s[76:77], v[246:247] op_sel_hi:[1,0,1] neg_lo:[0,0,1] neg_hi:[0,0,1]
	v_pk_fma_f32 v[246:247], v[84:85], s[12:13], v[246:247] op_sel_hi:[1,0,1]
	v_pk_fma_f32 v[84:85], v[84:85], s[76:77], v[246:247] op_sel_hi:[1,0,1]
	v_pk_mul_f32 v[244:245], v[86:87], s[76:77] op_sel_hi:[1,0]
	v_pk_fma_f32 v[244:245], v[86:87], s[76:77], v[244:245] op_sel_hi:[1,0,1] neg_lo:[0,0,1] neg_hi:[0,0,1]
	v_pk_fma_f32 v[244:245], v[86:87], s[12:13], v[244:245] op_sel_hi:[1,0,1]
	v_pk_fma_f32 v[86:87], v[86:87], s[76:77], v[244:245] op_sel_hi:[1,0,1]
	v_pk_mul_f32 v[246:247], v[88:89], s[76:77] op_sel_hi:[1,0]
	v_pk_fma_f32 v[246:247], v[88:89], s[76:77], v[246:247] op_sel_hi:[1,0,1] neg_lo:[0,0,1] neg_hi:[0,0,1]
	v_pk_fma_f32 v[246:247], v[88:89], s[12:13], v[246:247] op_sel_hi:[1,0,1]
	v_pk_fma_f32 v[88:89], v[88:89], s[76:77], v[246:247] op_sel_hi:[1,0,1]
	s_mov_b64 s[4:5], 0
	global_store_dwordx4 v[100:101], v[82:85], off
	global_store_dwordx4 v[100:101], v[86:89], off offset:16

.LBB0_873:
	s_andn2_b64 vcc, exec, s[0:1]
	s_cbranch_vccnz .LBB0_890
	v_mad_i64_i32 v[92:93], s[0:1], v82, s33, v[122:123]
	s_cmp_gt_i32 s71, 8
	s_mov_b64 s[0:1], -1
	s_cbranch_scc1 .LBB0_880
	s_cmp_lt_u32 s73, 5
	s_cselect_b64 s[0:1], -1, 0
	s_cmp_gt_u32 s73, 4
	s_cbranch_scc0 .LBB0_880
	s_andn2_b64 vcc, exec, s[28:29]
	s_mov_b64 s[4:5], -1
	s_cbranch_vccnz .LBB0_878
	s_mov_b32 s4, 0x3fb8aa3b
	s_mov_b32 s76, 0x3f317217
	s_mov_b32 s12, 0x3377d1cf
	v_lshl_add_u64 v[94:95], v[92:93], 2, s[86:87]
	v_pk_mul_f32 v[66:67], v[90:91], s[4:5] op_sel_hi:[1,0]
	v_pk_mul_f32 v[68:69], v[88:89], s[4:5] op_sel_hi:[1,0]
	v_pk_mul_f32 v[70:71], v[86:87], s[4:5] op_sel_hi:[1,0]
	v_pk_mul_f32 v[72:73], v[84:85], s[4:5] op_sel_hi:[1,0]
	v_exp_f32_e32 v66, v66
	v_exp_f32_e32 v67, v67
	v_exp_f32_e32 v68, v68
	v_exp_f32_e32 v69, v69
	v_exp_f32_e32 v70, v70
	v_exp_f32_e32 v71, v71
	v_exp_f32_e32 v72, v72
	v_exp_f32_e32 v73, v73
	v_pk_add_f32 v[66:67], v[66:67], 1.0 op_sel_hi:[1,0]
	v_pk_add_f32 v[68:69], v[68:69], 1.0 op_sel_hi:[1,0]
	v_pk_add_f32 v[70:71], v[70:71], 1.0 op_sel_hi:[1,0]
	v_pk_add_f32 v[72:73], v[72:73], 1.0 op_sel_hi:[1,0]
	v_rcp_f32_e32 v66, v66
	v_rcp_f32_e32 v67, v67
	v_rcp_f32_e32 v68, v68
	v_rcp_f32_e32 v69, v69
	v_rcp_f32_e32 v70, v70
	v_rcp_f32_e32 v71, v71
	v_rcp_f32_e32 v72, v72
	v_rcp_f32_e32 v73, v73
	v_pk_mul_f32 v[66:67], v[66:67], v[220:221]
	v_pk_mul_f32 v[68:69], v[68:69], v[222:223]
	v_pk_mul_f32 v[70:71], v[70:71], v[224:225]
	v_pk_mul_f32 v[72:73], v[72:73], v[226:227]
	v_min_f32_e32 v66, 0x3f7fffef, v66
	v_min_f32_e32 v67, 0x3f7fffef, v67
	v_min_f32_e32 v68, 0x3f7fffef, v68
	v_min_f32_e32 v69, 0x3f7fffef, v69
	v_min_f32_e32 v70, 0x3f7fffef, v70
	v_min_f32_e32 v71, 0x3f7fffef, v71
	v_min_f32_e32 v72, 0x3f7fffef, v72
	v_min_f32_e32 v73, 0x3f7fffef, v73
	v_pk_add_f32 v[66:67], v[66:67], 1.0 op_sel_hi:[1,0] neg_lo:[1,0] neg_hi:[1,0]
	v_pk_add_f32 v[68:69], v[68:69], 1.0 op_sel_hi:[1,0] neg_lo:[1,0] neg_hi:[1,0]
	v_pk_add_f32 v[70:71], v[70:71], 1.0 op_sel_hi:[1,0] neg_lo:[1,0] neg_hi:[1,0]
	v_pk_add_f32 v[72:73], v[72:73], 1.0 op_sel_hi:[1,0] neg_lo:[1,0] neg_hi:[1,0]
	v_log_f32_e32 v66, v66
	v_log_f32_e32 v67, v67
	v_log_f32_e32 v68, v68
	v_log_f32_e32 v69, v69
	v_log_f32_e32 v70, v70
	v_log_f32_e32 v71, v71
	v_log_f32_e32 v72, v72
	v_log_f32_e32 v73, v73
	v_pk_mul_f32 v[244:245], v[66:67], s[76:77] op_sel_hi:[1,0]
	v_pk_fma_f32 v[244:245], v[66:67], s[76:77], v[244:245] op_sel_hi:[1,0,1] neg_lo:[0,0,1] neg_hi:[0,0,1]
	v_pk_fma_f32 v[244:245], v[66:67], s[12:13], v[244:245] op_sel_hi:[1,0,1]
	v_pk_fma_f32 v[66:67], v[66:67], s[76:77], v[244:245] op_sel_hi:[1,0,1]
	v_pk_mul_f32 v[246:247], v[68:69], s[76:77] op_sel_hi:[1,0]
	v_pk_fma_f32 v[246:247], v[68:69], s[76:77], v[246:247] op_sel_hi:[1,0,1] neg_lo:[0,0,1] neg_hi:[0,0,1]
	v_pk_fma_f32 v[246:247], v[68:69], s[12:13], v[246:247] op_sel_hi:[1,0,1]
	v_pk_fma_f32 v[68:69], v[68:69], s[76:77], v[246:247] op_sel_hi:[1,0,1]
	v_pk_mul_f32 v[244:245], v[70:71], s[76:77] op_sel_hi:[1,0]
	v_pk_fma_f32 v[244:245], v[70:71], s[76:77], v[244:245] op_sel_hi:[1,0,1] neg_lo:[0,0,1] neg_hi:[0,0,1]
	v_pk_fma_f32 v[244:245], v[70:71], s[12:13], v[244:245] op_sel_hi:[1,0,1]
	v_pk_fma_f32 v[70:71], v[70:71], s[76:77], v[244:245] op_sel_hi:[1,0,1]
	v_pk_mul_f32 v[246:247], v[72:73], s[76:77] op_sel_hi:[1,0]
	v_pk_fma_f32 v[246:247], v[72:73], s[76:77], v[246:247] op_sel_hi:[1,0,1] neg_lo:[0,0,1] neg_hi:[0,0,1]
	v_pk_fma_f32 v[246:247], v[72:73], s[12:13], v[246:247] op_sel_hi:[1,0,1]
	v_pk_fma_f32 v[72:73], v[72:73], s[76:77], v[246:247] op_sel_hi:[1,0,1]
	s_mov_b64 s[4:5], 0
	global_store_dwordx4 v[94:95], v[66:69], off
	global_store_dwordx4 v[94:95], v[70:73], off offset:16

.LBB0_882:
	s_nop 1
	v_mad_i64_i32 v[66:67], s[0:1], v82, s33, 0
	v_lshl_add_u64 v[82:83], v[66:67], 0, v[124:125]
	s_cmp_gt_i32 s71, 8
	s_mov_b64 s[0:1], -1
	s_cbranch_scc1 .LBB0_888
	s_cmp_lt_u32 s73, 5
	s_cselect_b64 s[0:1], -1, 0
	s_cmp_gt_u32 s73, 4
	s_cbranch_scc0 .LBB0_888
	s_andn2_b64 vcc, exec, s[28:29]
	s_mov_b64 s[4:5], -1
	s_cbranch_vccnz .LBB0_886
	s_mov_b32 s4, 0x3fb8aa3b
	s_mov_b32 s76, 0x3f317217
	s_mov_b32 s12, 0x3377d1cf
	v_lshl_add_u64 v[84:85], v[82:83], 2, s[86:87]
	v_pk_mul_f32 v[66:67], v[80:81], s[4:5] op_sel_hi:[1,0]
	v_pk_mul_f32 v[68:69], v[78:79], s[4:5] op_sel_hi:[1,0]
	v_pk_mul_f32 v[70:71], v[76:77], s[4:5] op_sel_hi:[1,0]
	v_pk_mul_f32 v[72:73], v[74:75], s[4:5] op_sel_hi:[1,0]
	v_exp_f32_e32 v66, v66
	v_exp_f32_e32 v67, v67
	v_exp_f32_e32 v68, v68
	v_exp_f32_e32 v69, v69
	v_exp_f32_e32 v70, v70
	v_exp_f32_e32 v71, v71
	v_exp_f32_e32 v72, v72
	v_exp_f32_e32 v73, v73
	v_pk_add_f32 v[66:67], v[66:67], 1.0 op_sel_hi:[1,0]
	v_pk_add_f32 v[68:69], v[68:69], 1.0 op_sel_hi:[1,0]
	v_pk_add_f32 v[70:71], v[70:71], 1.0 op_sel_hi:[1,0]
	v_pk_add_f32 v[72:73], v[72:73], 1.0 op_sel_hi:[1,0]
	v_rcp_f32_e32 v66, v66
	v_rcp_f32_e32 v67, v67
	v_rcp_f32_e32 v68, v68
	v_rcp_f32_e32 v69, v69
	v_rcp_f32_e32 v70, v70
	v_rcp_f32_e32 v71, v71
	v_rcp_f32_e32 v72, v72
	v_rcp_f32_e32 v73, v73
	v_pk_mul_f32 v[66:67], v[66:67], v[228:229]
	v_pk_mul_f32 v[68:69], v[68:69], v[230:231]
	v_pk_mul_f32 v[70:71], v[70:71], v[232:233]
	v_pk_mul_f32 v[72:73], v[72:73], v[234:235]
	v_min_f32_e32 v66, 0x3f7fffef, v66
	v_min_f32_e32 v67, 0x3f7fffef, v67
	v_min_f32_e32 v68, 0x3f7fffef, v68
	v_min_f32_e32 v69, 0x3f7fffef, v69
	v_min_f32_e32 v70, 0x3f7fffef, v70
	v_min_f32_e32 v71, 0x3f7fffef, v71
	v_min_f32_e32 v72, 0x3f7fffef, v72
	v_min_f32_e32 v73, 0x3f7fffef, v73
	v_pk_add_f32 v[66:67], v[66:67], 1.0 op_sel_hi:[1,0] neg_lo:[1,0] neg_hi:[1,0]
	v_pk_add_f32 v[68:69], v[68:69], 1.0 op_sel_hi:[1,0] neg_lo:[1,0] neg_hi:[1,0]
	v_pk_add_f32 v[70:71], v[70:71], 1.0 op_sel_hi:[1,0] neg_lo:[1,0] neg_hi:[1,0]
	v_pk_add_f32 v[72:73], v[72:73], 1.0 op_sel_hi:[1,0] neg_lo:[1,0] neg_hi:[1,0]
	v_log_f32_e32 v66, v66
	v_log_f32_e32 v67, v67
	v_log_f32_e32 v68, v68
	v_log_f32_e32 v69, v69
	v_log_f32_e32 v70, v70
	v_log_f32_e32 v71, v71
	v_log_f32_e32 v72, v72
	v_log_f32_e32 v73, v73
	v_pk_mul_f32 v[244:245], v[66:67], s[76:77] op_sel_hi:[1,0]
	v_pk_fma_f32 v[244:245], v[66:67], s[76:77], v[244:245] op_sel_hi:[1,0,1] neg_lo:[0,0,1] neg_hi:[0,0,1]
	v_pk_fma_f32 v[244:245], v[66:67], s[12:13], v[244:245] op_sel_hi:[1,0,1]
	v_pk_fma_f32 v[66:67], v[66:67], s[76:77], v[244:245] op_sel_hi:[1,0,1]
	v_pk_mul_f32 v[246:247], v[68:69], s[76:77] op_sel_hi:[1,0]
	v_pk_fma_f32 v[246:247], v[68:69], s[76:77], v[246:247] op_sel_hi:[1,0,1] neg_lo:[0,0,1] neg_hi:[0,0,1]
	v_pk_fma_f32 v[246:247], v[68:69], s[12:13], v[246:247] op_sel_hi:[1,0,1]
	v_pk_fma_f32 v[68:69], v[68:69], s[76:77], v[246:247] op_sel_hi:[1,0,1]
	v_pk_mul_f32 v[244:245], v[70:71], s[76:77] op_sel_hi:[1,0]
	v_pk_fma_f32 v[244:245], v[70:71], s[76:77], v[244:245] op_sel_hi:[1,0,1] neg_lo:[0,0,1] neg_hi:[0,0,1]
	v_pk_fma_f32 v[244:245], v[70:71], s[12:13], v[244:245] op_sel_hi:[1,0,1]
	v_pk_fma_f32 v[70:71], v[70:71], s[76:77], v[244:245] op_sel_hi:[1,0,1]
	v_pk_mul_f32 v[246:247], v[72:73], s[76:77] op_sel_hi:[1,0]
	v_pk_fma_f32 v[246:247], v[72:73], s[76:77], v[246:247] op_sel_hi:[1,0,1] neg_lo:[0,0,1] neg_hi:[0,0,1]
	v_pk_fma_f32 v[246:247], v[72:73], s[12:13], v[246:247] op_sel_hi:[1,0,1]
	v_pk_fma_f32 v[72:73], v[72:73], s[76:77], v[246:247] op_sel_hi:[1,0,1]
	s_mov_b64 s[4:5], 0
	global_store_dwordx4 v[84:85], v[66:69], off
	global_store_dwordx4 v[84:85], v[70:73], off offset:16

.LBB0_892:
	s_andn2_b64 vcc, exec, s[0:1]
	s_cbranch_vccnz .LBB0_909
	v_mad_i64_i32 v[76:77], s[0:1], v66, s33, v[122:123]
	s_cmp_gt_i32 s71, 8
	s_mov_b64 s[0:1], -1
	s_cbranch_scc1 .LBB0_899
	s_cmp_lt_u32 s73, 5
	s_cselect_b64 s[0:1], -1, 0
	s_cmp_gt_u32 s73, 4
	s_cbranch_scc0 .LBB0_899
	s_andn2_b64 vcc, exec, s[28:29]
	s_mov_b64 s[4:5], -1
	s_cbranch_vccnz .LBB0_897
	s_mov_b32 s4, 0x3fb8aa3b
	s_mov_b32 s76, 0x3f317217
	s_mov_b32 s12, 0x3377d1cf
	v_lshl_add_u64 v[78:79], v[76:77], 2, s[86:87]
	v_pk_mul_f32 v[50:51], v[74:75], s[4:5] op_sel_hi:[1,0]
	v_pk_mul_f32 v[52:53], v[72:73], s[4:5] op_sel_hi:[1,0]
	v_pk_mul_f32 v[54:55], v[70:71], s[4:5] op_sel_hi:[1,0]
	v_pk_mul_f32 v[56:57], v[68:69], s[4:5] op_sel_hi:[1,0]
	v_exp_f32_e32 v50, v50
	v_exp_f32_e32 v51, v51
	v_exp_f32_e32 v52, v52
	v_exp_f32_e32 v53, v53
	v_exp_f32_e32 v54, v54
	v_exp_f32_e32 v55, v55
	v_exp_f32_e32 v56, v56
	v_exp_f32_e32 v57, v57
	v_pk_add_f32 v[50:51], v[50:51], 1.0 op_sel_hi:[1,0]
	v_pk_add_f32 v[52:53], v[52:53], 1.0 op_sel_hi:[1,0]
	v_pk_add_f32 v[54:55], v[54:55], 1.0 op_sel_hi:[1,0]
	v_pk_add_f32 v[56:57], v[56:57], 1.0 op_sel_hi:[1,0]
	v_rcp_f32_e32 v50, v50
	v_rcp_f32_e32 v51, v51
	v_rcp_f32_e32 v52, v52
	v_rcp_f32_e32 v53, v53
	v_rcp_f32_e32 v54, v54
	v_rcp_f32_e32 v55, v55
	v_rcp_f32_e32 v56, v56
	v_rcp_f32_e32 v57, v57
	v_pk_mul_f32 v[50:51], v[50:51], v[220:221]
	v_pk_mul_f32 v[52:53], v[52:53], v[222:223]
	v_pk_mul_f32 v[54:55], v[54:55], v[224:225]
	v_pk_mul_f32 v[56:57], v[56:57], v[226:227]
	v_min_f32_e32 v50, 0x3f7fffef, v50
	v_min_f32_e32 v51, 0x3f7fffef, v51
	v_min_f32_e32 v52, 0x3f7fffef, v52
	v_min_f32_e32 v53, 0x3f7fffef, v53
	v_min_f32_e32 v54, 0x3f7fffef, v54
	v_min_f32_e32 v55, 0x3f7fffef, v55
	v_min_f32_e32 v56, 0x3f7fffef, v56
	v_min_f32_e32 v57, 0x3f7fffef, v57
	v_pk_add_f32 v[50:51], v[50:51], 1.0 op_sel_hi:[1,0] neg_lo:[1,0] neg_hi:[1,0]
	v_pk_add_f32 v[52:53], v[52:53], 1.0 op_sel_hi:[1,0] neg_lo:[1,0] neg_hi:[1,0]
	v_pk_add_f32 v[54:55], v[54:55], 1.0 op_sel_hi:[1,0] neg_lo:[1,0] neg_hi:[1,0]
	v_pk_add_f32 v[56:57], v[56:57], 1.0 op_sel_hi:[1,0] neg_lo:[1,0] neg_hi:[1,0]
	v_log_f32_e32 v50, v50
	v_log_f32_e32 v51, v51
	v_log_f32_e32 v52, v52
	v_log_f32_e32 v53, v53
	v_log_f32_e32 v54, v54
	v_log_f32_e32 v55, v55
	v_log_f32_e32 v56, v56
	v_log_f32_e32 v57, v57
	v_pk_mul_f32 v[244:245], v[50:51], s[76:77] op_sel_hi:[1,0]
	v_pk_fma_f32 v[244:245], v[50:51], s[76:77], v[244:245] op_sel_hi:[1,0,1] neg_lo:[0,0,1] neg_hi:[0,0,1]
	v_pk_fma_f32 v[244:245], v[50:51], s[12:13], v[244:245] op_sel_hi:[1,0,1]
	v_pk_fma_f32 v[50:51], v[50:51], s[76:77], v[244:245] op_sel_hi:[1,0,1]
	v_pk_mul_f32 v[246:247], v[52:53], s[76:77] op_sel_hi:[1,0]
	v_pk_fma_f32 v[246:247], v[52:53], s[76:77], v[246:247] op_sel_hi:[1,0,1] neg_lo:[0,0,1] neg_hi:[0,0,1]
	v_pk_fma_f32 v[246:247], v[52:53], s[12:13], v[246:247] op_sel_hi:[1,0,1]
	v_pk_fma_f32 v[52:53], v[52:53], s[76:77], v[246:247] op_sel_hi:[1,0,1]
	v_pk_mul_f32 v[244:245], v[54:55], s[76:77] op_sel_hi:[1,0]
	v_pk_fma_f32 v[244:245], v[54:55], s[76:77], v[244:245] op_sel_hi:[1,0,1] neg_lo:[0,0,1] neg_hi:[0,0,1]
	v_pk_fma_f32 v[244:245], v[54:55], s[12:13], v[244:245] op_sel_hi:[1,0,1]
	v_pk_fma_f32 v[54:55], v[54:55], s[76:77], v[244:245] op_sel_hi:[1,0,1]
	v_pk_mul_f32 v[246:247], v[56:57], s[76:77] op_sel_hi:[1,0]
	v_pk_fma_f32 v[246:247], v[56:57], s[76:77], v[246:247] op_sel_hi:[1,0,1] neg_lo:[0,0,1] neg_hi:[0,0,1]
	v_pk_fma_f32 v[246:247], v[56:57], s[12:13], v[246:247] op_sel_hi:[1,0,1]
	v_pk_fma_f32 v[56:57], v[56:57], s[76:77], v[246:247] op_sel_hi:[1,0,1]
	s_mov_b64 s[4:5], 0
	global_store_dwordx4 v[78:79], v[50:53], off
	global_store_dwordx4 v[78:79], v[54:57], off offset:16

.LBB0_901:
	s_nop 1
	v_mad_i64_i32 v[50:51], s[0:1], v66, s33, 0
	v_lshl_add_u64 v[66:67], v[50:51], 0, v[124:125]
	s_cmp_gt_i32 s71, 8
	s_mov_b64 s[0:1], -1
	s_cbranch_scc1 .LBB0_907
	s_cmp_lt_u32 s73, 5
	s_cselect_b64 s[0:1], -1, 0
	s_cmp_gt_u32 s73, 4
	s_cbranch_scc0 .LBB0_907
	s_andn2_b64 vcc, exec, s[28:29]
	s_mov_b64 s[4:5], -1
	s_cbranch_vccnz .LBB0_905
	s_mov_b32 s4, 0x3fb8aa3b
	s_mov_b32 s76, 0x3f317217
	s_mov_b32 s12, 0x3377d1cf
	v_lshl_add_u64 v[68:69], v[66:67], 2, s[86:87]
	v_pk_mul_f32 v[50:51], v[64:65], s[4:5] op_sel_hi:[1,0]
	v_pk_mul_f32 v[52:53], v[62:63], s[4:5] op_sel_hi:[1,0]
	v_pk_mul_f32 v[54:55], v[60:61], s[4:5] op_sel_hi:[1,0]
	v_pk_mul_f32 v[56:57], v[58:59], s[4:5] op_sel_hi:[1,0]
	v_exp_f32_e32 v50, v50
	v_exp_f32_e32 v51, v51
	v_exp_f32_e32 v52, v52
	v_exp_f32_e32 v53, v53
	v_exp_f32_e32 v54, v54
	v_exp_f32_e32 v55, v55
	v_exp_f32_e32 v56, v56
	v_exp_f32_e32 v57, v57
	v_pk_add_f32 v[50:51], v[50:51], 1.0 op_sel_hi:[1,0]
	v_pk_add_f32 v[52:53], v[52:53], 1.0 op_sel_hi:[1,0]
	v_pk_add_f32 v[54:55], v[54:55], 1.0 op_sel_hi:[1,0]
	v_pk_add_f32 v[56:57], v[56:57], 1.0 op_sel_hi:[1,0]
	v_rcp_f32_e32 v50, v50
	v_rcp_f32_e32 v51, v51
	v_rcp_f32_e32 v52, v52
	v_rcp_f32_e32 v53, v53
	v_rcp_f32_e32 v54, v54
	v_rcp_f32_e32 v55, v55
	v_rcp_f32_e32 v56, v56
	v_rcp_f32_e32 v57, v57
	v_pk_mul_f32 v[50:51], v[50:51], v[228:229]
	v_pk_mul_f32 v[52:53], v[52:53], v[230:231]
	v_pk_mul_f32 v[54:55], v[54:55], v[232:233]
	v_pk_mul_f32 v[56:57], v[56:57], v[234:235]
	v_min_f32_e32 v50, 0x3f7fffef, v50
	v_min_f32_e32 v51, 0x3f7fffef, v51
	v_min_f32_e32 v52, 0x3f7fffef, v52
	v_min_f32_e32 v53, 0x3f7fffef, v53
	v_min_f32_e32 v54, 0x3f7fffef, v54
	v_min_f32_e32 v55, 0x3f7fffef, v55
	v_min_f32_e32 v56, 0x3f7fffef, v56
	v_min_f32_e32 v57, 0x3f7fffef, v57
	v_pk_add_f32 v[50:51], v[50:51], 1.0 op_sel_hi:[1,0] neg_lo:[1,0] neg_hi:[1,0]
	v_pk_add_f32 v[52:53], v[52:53], 1.0 op_sel_hi:[1,0] neg_lo:[1,0] neg_hi:[1,0]
	v_pk_add_f32 v[54:55], v[54:55], 1.0 op_sel_hi:[1,0] neg_lo:[1,0] neg_hi:[1,0]
	v_pk_add_f32 v[56:57], v[56:57], 1.0 op_sel_hi:[1,0] neg_lo:[1,0] neg_hi:[1,0]
	v_log_f32_e32 v50, v50
	v_log_f32_e32 v51, v51
	v_log_f32_e32 v52, v52
	v_log_f32_e32 v53, v53
	v_log_f32_e32 v54, v54
	v_log_f32_e32 v55, v55
	v_log_f32_e32 v56, v56
	v_log_f32_e32 v57, v57
	v_pk_mul_f32 v[244:245], v[50:51], s[76:77] op_sel_hi:[1,0]
	v_pk_fma_f32 v[244:245], v[50:51], s[76:77], v[244:245] op_sel_hi:[1,0,1] neg_lo:[0,0,1] neg_hi:[0,0,1]
	v_pk_fma_f32 v[244:245], v[50:51], s[12:13], v[244:245] op_sel_hi:[1,0,1]
	v_pk_fma_f32 v[50:51], v[50:51], s[76:77], v[244:245] op_sel_hi:[1,0,1]
	v_pk_mul_f32 v[246:247], v[52:53], s[76:77] op_sel_hi:[1,0]
	v_pk_fma_f32 v[246:247], v[52:53], s[76:77], v[246:247] op_sel_hi:[1,0,1] neg_lo:[0,0,1] neg_hi:[0,0,1]
	v_pk_fma_f32 v[246:247], v[52:53], s[12:13], v[246:247] op_sel_hi:[1,0,1]
	v_pk_fma_f32 v[52:53], v[52:53], s[76:77], v[246:247] op_sel_hi:[1,0,1]
	v_pk_mul_f32 v[244:245], v[54:55], s[76:77] op_sel_hi:[1,0]
	v_pk_fma_f32 v[244:245], v[54:55], s[76:77], v[244:245] op_sel_hi:[1,0,1] neg_lo:[0,0,1] neg_hi:[0,0,1]
	v_pk_fma_f32 v[244:245], v[54:55], s[12:13], v[244:245] op_sel_hi:[1,0,1]
	v_pk_fma_f32 v[54:55], v[54:55], s[76:77], v[244:245] op_sel_hi:[1,0,1]
	v_pk_mul_f32 v[246:247], v[56:57], s[76:77] op_sel_hi:[1,0]
	v_pk_fma_f32 v[246:247], v[56:57], s[76:77], v[246:247] op_sel_hi:[1,0,1] neg_lo:[0,0,1] neg_hi:[0,0,1]
	v_pk_fma_f32 v[246:247], v[56:57], s[12:13], v[246:247] op_sel_hi:[1,0,1]
	v_pk_fma_f32 v[56:57], v[56:57], s[76:77], v[246:247] op_sel_hi:[1,0,1]
	s_mov_b64 s[4:5], 0
	global_store_dwordx4 v[68:69], v[50:53], off
	global_store_dwordx4 v[68:69], v[54:57], off offset:16

.LBB0_911:
	s_andn2_b64 vcc, exec, s[0:1]
	s_cbranch_vccnz .LBB0_928
	v_mad_i64_i32 v[60:61], s[0:1], v50, s33, v[122:123]
	s_cmp_gt_i32 s71, 8
	s_mov_b64 s[0:1], -1
	s_cbranch_scc1 .LBB0_918
	s_cmp_lt_u32 s73, 5
	s_cselect_b64 s[0:1], -1, 0
	s_cmp_gt_u32 s73, 4
	s_cbranch_scc0 .LBB0_918
	s_andn2_b64 vcc, exec, s[28:29]
	s_mov_b64 s[4:5], -1
	s_cbranch_vccnz .LBB0_916
	s_mov_b32 s4, 0x3fb8aa3b
	s_mov_b32 s76, 0x3f317217
	s_mov_b32 s12, 0x3377d1cf
	v_lshl_add_u64 v[62:63], v[60:61], 2, s[86:87]
	v_pk_mul_f32 v[34:35], v[58:59], s[4:5] op_sel_hi:[1,0]
	v_pk_mul_f32 v[36:37], v[56:57], s[4:5] op_sel_hi:[1,0]
	v_pk_mul_f32 v[38:39], v[54:55], s[4:5] op_sel_hi:[1,0]
	v_pk_mul_f32 v[40:41], v[52:53], s[4:5] op_sel_hi:[1,0]
	v_exp_f32_e32 v34, v34
	v_exp_f32_e32 v35, v35
	v_exp_f32_e32 v36, v36
	v_exp_f32_e32 v37, v37
	v_exp_f32_e32 v38, v38
	v_exp_f32_e32 v39, v39
	v_exp_f32_e32 v40, v40
	v_exp_f32_e32 v41, v41
	v_pk_add_f32 v[34:35], v[34:35], 1.0 op_sel_hi:[1,0]
	v_pk_add_f32 v[36:37], v[36:37], 1.0 op_sel_hi:[1,0]
	v_pk_add_f32 v[38:39], v[38:39], 1.0 op_sel_hi:[1,0]
	v_pk_add_f32 v[40:41], v[40:41], 1.0 op_sel_hi:[1,0]
	v_rcp_f32_e32 v34, v34
	v_rcp_f32_e32 v35, v35
	v_rcp_f32_e32 v36, v36
	v_rcp_f32_e32 v37, v37
	v_rcp_f32_e32 v38, v38
	v_rcp_f32_e32 v39, v39
	v_rcp_f32_e32 v40, v40
	v_rcp_f32_e32 v41, v41
	v_pk_mul_f32 v[34:35], v[34:35], v[220:221]
	v_pk_mul_f32 v[36:37], v[36:37], v[222:223]
	v_pk_mul_f32 v[38:39], v[38:39], v[224:225]
	v_pk_mul_f32 v[40:41], v[40:41], v[226:227]
	v_min_f32_e32 v34, 0x3f7fffef, v34
	v_min_f32_e32 v35, 0x3f7fffef, v35
	v_min_f32_e32 v36, 0x3f7fffef, v36
	v_min_f32_e32 v37, 0x3f7fffef, v37
	v_min_f32_e32 v38, 0x3f7fffef, v38
	v_min_f32_e32 v39, 0x3f7fffef, v39
	v_min_f32_e32 v40, 0x3f7fffef, v40
	v_min_f32_e32 v41, 0x3f7fffef, v41
	v_pk_add_f32 v[34:35], v[34:35], 1.0 op_sel_hi:[1,0] neg_lo:[1,0] neg_hi:[1,0]
	v_pk_add_f32 v[36:37], v[36:37], 1.0 op_sel_hi:[1,0] neg_lo:[1,0] neg_hi:[1,0]
	v_pk_add_f32 v[38:39], v[38:39], 1.0 op_sel_hi:[1,0] neg_lo:[1,0] neg_hi:[1,0]
	v_pk_add_f32 v[40:41], v[40:41], 1.0 op_sel_hi:[1,0] neg_lo:[1,0] neg_hi:[1,0]
	v_log_f32_e32 v34, v34
	v_log_f32_e32 v35, v35
	v_log_f32_e32 v36, v36
	v_log_f32_e32 v37, v37
	v_log_f32_e32 v38, v38
	v_log_f32_e32 v39, v39
	v_log_f32_e32 v40, v40
	v_log_f32_e32 v41, v41
	v_pk_mul_f32 v[244:245], v[34:35], s[76:77] op_sel_hi:[1,0]
	v_pk_fma_f32 v[244:245], v[34:35], s[76:77], v[244:245] op_sel_hi:[1,0,1] neg_lo:[0,0,1] neg_hi:[0,0,1]
	v_pk_fma_f32 v[244:245], v[34:35], s[12:13], v[244:245] op_sel_hi:[1,0,1]
	v_pk_fma_f32 v[34:35], v[34:35], s[76:77], v[244:245] op_sel_hi:[1,0,1]
	v_pk_mul_f32 v[246:247], v[36:37], s[76:77] op_sel_hi:[1,0]
	v_pk_fma_f32 v[246:247], v[36:37], s[76:77], v[246:247] op_sel_hi:[1,0,1] neg_lo:[0,0,1] neg_hi:[0,0,1]
	v_pk_fma_f32 v[246:247], v[36:37], s[12:13], v[246:247] op_sel_hi:[1,0,1]
	v_pk_fma_f32 v[36:37], v[36:37], s[76:77], v[246:247] op_sel_hi:[1,0,1]
	v_pk_mul_f32 v[244:245], v[38:39], s[76:77] op_sel_hi:[1,0]
	v_pk_fma_f32 v[244:245], v[38:39], s[76:77], v[244:245] op_sel_hi:[1,0,1] neg_lo:[0,0,1] neg_hi:[0,0,1]
	v_pk_fma_f32 v[244:245], v[38:39], s[12:13], v[244:245] op_sel_hi:[1,0,1]
	v_pk_fma_f32 v[38:39], v[38:39], s[76:77], v[244:245] op_sel_hi:[1,0,1]
	v_pk_mul_f32 v[246:247], v[40:41], s[76:77] op_sel_hi:[1,0]
	v_pk_fma_f32 v[246:247], v[40:41], s[76:77], v[246:247] op_sel_hi:[1,0,1] neg_lo:[0,0,1] neg_hi:[0,0,1]
	v_pk_fma_f32 v[246:247], v[40:41], s[12:13], v[246:247] op_sel_hi:[1,0,1]
	v_pk_fma_f32 v[40:41], v[40:41], s[76:77], v[246:247] op_sel_hi:[1,0,1]
	s_mov_b64 s[4:5], 0
	global_store_dwordx4 v[62:63], v[34:37], off
	global_store_dwordx4 v[62:63], v[38:41], off offset:16

.LBB0_920:
	s_nop 1
	v_mad_i64_i32 v[34:35], s[0:1], v50, s33, 0
	v_lshl_add_u64 v[50:51], v[34:35], 0, v[124:125]
	s_cmp_gt_i32 s71, 8
	s_mov_b64 s[0:1], -1
	s_cbranch_scc1 .LBB0_926
	s_cmp_lt_u32 s73, 5
	s_cselect_b64 s[0:1], -1, 0
	s_cmp_gt_u32 s73, 4
	s_cbranch_scc0 .LBB0_926
	s_andn2_b64 vcc, exec, s[28:29]
	s_mov_b64 s[4:5], -1
	s_cbranch_vccnz .LBB0_924
	s_mov_b32 s4, 0x3fb8aa3b
	s_mov_b32 s76, 0x3f317217
	s_mov_b32 s12, 0x3377d1cf
	v_lshl_add_u64 v[52:53], v[50:51], 2, s[86:87]
	v_pk_mul_f32 v[34:35], v[48:49], s[4:5] op_sel_hi:[1,0]
	v_pk_mul_f32 v[36:37], v[46:47], s[4:5] op_sel_hi:[1,0]
	v_pk_mul_f32 v[38:39], v[44:45], s[4:5] op_sel_hi:[1,0]
	v_pk_mul_f32 v[40:41], v[42:43], s[4:5] op_sel_hi:[1,0]
	v_exp_f32_e32 v34, v34
	v_exp_f32_e32 v35, v35
	v_exp_f32_e32 v36, v36
	v_exp_f32_e32 v37, v37
	v_exp_f32_e32 v38, v38
	v_exp_f32_e32 v39, v39
	v_exp_f32_e32 v40, v40
	v_exp_f32_e32 v41, v41
	v_pk_add_f32 v[34:35], v[34:35], 1.0 op_sel_hi:[1,0]
	v_pk_add_f32 v[36:37], v[36:37], 1.0 op_sel_hi:[1,0]
	v_pk_add_f32 v[38:39], v[38:39], 1.0 op_sel_hi:[1,0]
	v_pk_add_f32 v[40:41], v[40:41], 1.0 op_sel_hi:[1,0]
	v_rcp_f32_e32 v34, v34
	v_rcp_f32_e32 v35, v35
	v_rcp_f32_e32 v36, v36
	v_rcp_f32_e32 v37, v37
	v_rcp_f32_e32 v38, v38
	v_rcp_f32_e32 v39, v39
	v_rcp_f32_e32 v40, v40
	v_rcp_f32_e32 v41, v41
	v_pk_mul_f32 v[34:35], v[34:35], v[228:229]
	v_pk_mul_f32 v[36:37], v[36:37], v[230:231]
	v_pk_mul_f32 v[38:39], v[38:39], v[232:233]
	v_pk_mul_f32 v[40:41], v[40:41], v[234:235]
	v_min_f32_e32 v34, 0x3f7fffef, v34
	v_min_f32_e32 v35, 0x3f7fffef, v35
	v_min_f32_e32 v36, 0x3f7fffef, v36
	v_min_f32_e32 v37, 0x3f7fffef, v37
	v_min_f32_e32 v38, 0x3f7fffef, v38
	v_min_f32_e32 v39, 0x3f7fffef, v39
	v_min_f32_e32 v40, 0x3f7fffef, v40
	v_min_f32_e32 v41, 0x3f7fffef, v41
	v_pk_add_f32 v[34:35], v[34:35], 1.0 op_sel_hi:[1,0] neg_lo:[1,0] neg_hi:[1,0]
	v_pk_add_f32 v[36:37], v[36:37], 1.0 op_sel_hi:[1,0] neg_lo:[1,0] neg_hi:[1,0]
	v_pk_add_f32 v[38:39], v[38:39], 1.0 op_sel_hi:[1,0] neg_lo:[1,0] neg_hi:[1,0]
	v_pk_add_f32 v[40:41], v[40:41], 1.0 op_sel_hi:[1,0] neg_lo:[1,0] neg_hi:[1,0]
	v_log_f32_e32 v34, v34
	v_log_f32_e32 v35, v35
	v_log_f32_e32 v36, v36
	v_log_f32_e32 v37, v37
	v_log_f32_e32 v38, v38
	v_log_f32_e32 v39, v39
	v_log_f32_e32 v40, v40
	v_log_f32_e32 v41, v41
	v_pk_mul_f32 v[244:245], v[34:35], s[76:77] op_sel_hi:[1,0]
	v_pk_fma_f32 v[244:245], v[34:35], s[76:77], v[244:245] op_sel_hi:[1,0,1] neg_lo:[0,0,1] neg_hi:[0,0,1]
	v_pk_fma_f32 v[244:245], v[34:35], s[12:13], v[244:245] op_sel_hi:[1,0,1]
	v_pk_fma_f32 v[34:35], v[34:35], s[76:77], v[244:245] op_sel_hi:[1,0,1]
	v_pk_mul_f32 v[246:247], v[36:37], s[76:77] op_sel_hi:[1,0]
	v_pk_fma_f32 v[246:247], v[36:37], s[76:77], v[246:247] op_sel_hi:[1,0,1] neg_lo:[0,0,1] neg_hi:[0,0,1]
	v_pk_fma_f32 v[246:247], v[36:37], s[12:13], v[246:247] op_sel_hi:[1,0,1]
	v_pk_fma_f32 v[36:37], v[36:37], s[76:77], v[246:247] op_sel_hi:[1,0,1]
	v_pk_mul_f32 v[244:245], v[38:39], s[76:77] op_sel_hi:[1,0]
	v_pk_fma_f32 v[244:245], v[38:39], s[76:77], v[244:245] op_sel_hi:[1,0,1] neg_lo:[0,0,1] neg_hi:[0,0,1]
	v_pk_fma_f32 v[244:245], v[38:39], s[12:13], v[244:245] op_sel_hi:[1,0,1]
	v_pk_fma_f32 v[38:39], v[38:39], s[76:77], v[244:245] op_sel_hi:[1,0,1]
	v_pk_mul_f32 v[246:247], v[40:41], s[76:77] op_sel_hi:[1,0]
	v_pk_fma_f32 v[246:247], v[40:41], s[76:77], v[246:247] op_sel_hi:[1,0,1] neg_lo:[0,0,1] neg_hi:[0,0,1]
	v_pk_fma_f32 v[246:247], v[40:41], s[12:13], v[246:247] op_sel_hi:[1,0,1]
	v_pk_fma_f32 v[40:41], v[40:41], s[76:77], v[246:247] op_sel_hi:[1,0,1]
	s_mov_b64 s[4:5], 0
	global_store_dwordx4 v[52:53], v[34:37], off
	global_store_dwordx4 v[52:53], v[38:41], off offset:16

.LBB0_930:
	s_andn2_b64 vcc, exec, s[0:1]
	s_cbranch_vccnz .LBB0_947
	v_mad_i64_i32 v[44:45], s[0:1], v34, s33, v[122:123]
	s_cmp_gt_i32 s71, 8
	s_mov_b64 s[0:1], -1
	s_cbranch_scc1 .LBB0_937
	s_cmp_lt_u32 s73, 5
	s_cselect_b64 s[0:1], -1, 0
	s_cmp_gt_u32 s73, 4
	s_cbranch_scc0 .LBB0_937
	s_andn2_b64 vcc, exec, s[28:29]
	s_mov_b64 s[4:5], -1
	s_cbranch_vccnz .LBB0_935
	s_mov_b32 s4, 0x3fb8aa3b
	s_mov_b32 s76, 0x3f317217
	s_mov_b32 s12, 0x3377d1cf
	v_lshl_add_u64 v[46:47], v[44:45], 2, s[86:87]
	v_pk_mul_f32 v[18:19], v[42:43], s[4:5] op_sel_hi:[1,0]
	v_pk_mul_f32 v[20:21], v[40:41], s[4:5] op_sel_hi:[1,0]
	v_pk_mul_f32 v[22:23], v[38:39], s[4:5] op_sel_hi:[1,0]
	v_pk_mul_f32 v[24:25], v[36:37], s[4:5] op_sel_hi:[1,0]
	v_exp_f32_e32 v18, v18
	v_exp_f32_e32 v19, v19
	v_exp_f32_e32 v20, v20
	v_exp_f32_e32 v21, v21
	v_exp_f32_e32 v22, v22
	v_exp_f32_e32 v23, v23
	v_exp_f32_e32 v24, v24
	v_exp_f32_e32 v25, v25
	v_pk_add_f32 v[18:19], v[18:19], 1.0 op_sel_hi:[1,0]
	v_pk_add_f32 v[20:21], v[20:21], 1.0 op_sel_hi:[1,0]
	v_pk_add_f32 v[22:23], v[22:23], 1.0 op_sel_hi:[1,0]
	v_pk_add_f32 v[24:25], v[24:25], 1.0 op_sel_hi:[1,0]
	v_rcp_f32_e32 v18, v18
	v_rcp_f32_e32 v19, v19
	v_rcp_f32_e32 v20, v20
	v_rcp_f32_e32 v21, v21
	v_rcp_f32_e32 v22, v22
	v_rcp_f32_e32 v23, v23
	v_rcp_f32_e32 v24, v24
	v_rcp_f32_e32 v25, v25
	v_pk_mul_f32 v[18:19], v[18:19], v[220:221]
	v_pk_mul_f32 v[20:21], v[20:21], v[222:223]
	v_pk_mul_f32 v[22:23], v[22:23], v[224:225]
	v_pk_mul_f32 v[24:25], v[24:25], v[226:227]
	v_min_f32_e32 v18, 0x3f7fffef, v18
	v_min_f32_e32 v19, 0x3f7fffef, v19
	v_min_f32_e32 v20, 0x3f7fffef, v20
	v_min_f32_e32 v21, 0x3f7fffef, v21
	v_min_f32_e32 v22, 0x3f7fffef, v22
	v_min_f32_e32 v23, 0x3f7fffef, v23
	v_min_f32_e32 v24, 0x3f7fffef, v24
	v_min_f32_e32 v25, 0x3f7fffef, v25
	v_pk_add_f32 v[18:19], v[18:19], 1.0 op_sel_hi:[1,0] neg_lo:[1,0] neg_hi:[1,0]
	v_pk_add_f32 v[20:21], v[20:21], 1.0 op_sel_hi:[1,0] neg_lo:[1,0] neg_hi:[1,0]
	v_pk_add_f32 v[22:23], v[22:23], 1.0 op_sel_hi:[1,0] neg_lo:[1,0] neg_hi:[1,0]
	v_pk_add_f32 v[24:25], v[24:25], 1.0 op_sel_hi:[1,0] neg_lo:[1,0] neg_hi:[1,0]
	v_log_f32_e32 v18, v18
	v_log_f32_e32 v19, v19
	v_log_f32_e32 v20, v20
	v_log_f32_e32 v21, v21
	v_log_f32_e32 v22, v22
	v_log_f32_e32 v23, v23
	v_log_f32_e32 v24, v24
	v_log_f32_e32 v25, v25
	v_pk_mul_f32 v[244:245], v[18:19], s[76:77] op_sel_hi:[1,0]
	v_pk_fma_f32 v[244:245], v[18:19], s[76:77], v[244:245] op_sel_hi:[1,0,1] neg_lo:[0,0,1] neg_hi:[0,0,1]
	v_pk_fma_f32 v[244:245], v[18:19], s[12:13], v[244:245] op_sel_hi:[1,0,1]
	v_pk_fma_f32 v[18:19], v[18:19], s[76:77], v[244:245] op_sel_hi:[1,0,1]
	v_pk_mul_f32 v[246:247], v[20:21], s[76:77] op_sel_hi:[1,0]
	v_pk_fma_f32 v[246:247], v[20:21], s[76:77], v[246:247] op_sel_hi:[1,0,1] neg_lo:[0,0,1] neg_hi:[0,0,1]
	v_pk_fma_f32 v[246:247], v[20:21], s[12:13], v[246:247] op_sel_hi:[1,0,1]
	v_pk_fma_f32 v[20:21], v[20:21], s[76:77], v[246:247] op_sel_hi:[1,0,1]
	v_pk_mul_f32 v[244:245], v[22:23], s[76:77] op_sel_hi:[1,0]
	v_pk_fma_f32 v[244:245], v[22:23], s[76:77], v[244:245] op_sel_hi:[1,0,1] neg_lo:[0,0,1] neg_hi:[0,0,1]
	v_pk_fma_f32 v[244:245], v[22:23], s[12:13], v[244:245] op_sel_hi:[1,0,1]
	v_pk_fma_f32 v[22:23], v[22:23], s[76:77], v[244:245] op_sel_hi:[1,0,1]
	v_pk_mul_f32 v[246:247], v[24:25], s[76:77] op_sel_hi:[1,0]
	v_pk_fma_f32 v[246:247], v[24:25], s[76:77], v[246:247] op_sel_hi:[1,0,1] neg_lo:[0,0,1] neg_hi:[0,0,1]
	v_pk_fma_f32 v[246:247], v[24:25], s[12:13], v[246:247] op_sel_hi:[1,0,1]
	v_pk_fma_f32 v[24:25], v[24:25], s[76:77], v[246:247] op_sel_hi:[1,0,1]
	s_mov_b64 s[4:5], 0
	global_store_dwordx4 v[46:47], v[18:21], off
	global_store_dwordx4 v[46:47], v[22:25], off offset:16

.LBB0_939:
	s_nop 1
	v_mad_i64_i32 v[18:19], s[0:1], v34, s33, 0
	v_lshl_add_u64 v[34:35], v[18:19], 0, v[124:125]
	s_cmp_gt_i32 s71, 8
	s_mov_b64 s[0:1], -1
	s_cbranch_scc1 .LBB0_945
	s_cmp_lt_u32 s73, 5
	s_cselect_b64 s[0:1], -1, 0
	s_cmp_gt_u32 s73, 4
	s_cbranch_scc0 .LBB0_945
	s_andn2_b64 vcc, exec, s[28:29]
	s_mov_b64 s[4:5], -1
	s_cbranch_vccnz .LBB0_943
	s_mov_b32 s4, 0x3fb8aa3b
	s_mov_b32 s76, 0x3f317217
	s_mov_b32 s12, 0x3377d1cf
	v_lshl_add_u64 v[36:37], v[34:35], 2, s[86:87]
	v_pk_mul_f32 v[18:19], v[32:33], s[4:5] op_sel_hi:[1,0]
	v_pk_mul_f32 v[20:21], v[30:31], s[4:5] op_sel_hi:[1,0]
	v_pk_mul_f32 v[22:23], v[28:29], s[4:5] op_sel_hi:[1,0]
	v_pk_mul_f32 v[24:25], v[26:27], s[4:5] op_sel_hi:[1,0]
	v_exp_f32_e32 v18, v18
	v_exp_f32_e32 v19, v19
	v_exp_f32_e32 v20, v20
	v_exp_f32_e32 v21, v21
	v_exp_f32_e32 v22, v22
	v_exp_f32_e32 v23, v23
	v_exp_f32_e32 v24, v24
	v_exp_f32_e32 v25, v25
	v_pk_add_f32 v[18:19], v[18:19], 1.0 op_sel_hi:[1,0]
	v_pk_add_f32 v[20:21], v[20:21], 1.0 op_sel_hi:[1,0]
	v_pk_add_f32 v[22:23], v[22:23], 1.0 op_sel_hi:[1,0]
	v_pk_add_f32 v[24:25], v[24:25], 1.0 op_sel_hi:[1,0]
	v_rcp_f32_e32 v18, v18
	v_rcp_f32_e32 v19, v19
	v_rcp_f32_e32 v20, v20
	v_rcp_f32_e32 v21, v21
	v_rcp_f32_e32 v22, v22
	v_rcp_f32_e32 v23, v23
	v_rcp_f32_e32 v24, v24
	v_rcp_f32_e32 v25, v25
	v_pk_mul_f32 v[18:19], v[18:19], v[228:229]
	v_pk_mul_f32 v[20:21], v[20:21], v[230:231]
	v_pk_mul_f32 v[22:23], v[22:23], v[232:233]
	v_pk_mul_f32 v[24:25], v[24:25], v[234:235]
	v_min_f32_e32 v18, 0x3f7fffef, v18
	v_min_f32_e32 v19, 0x3f7fffef, v19
	v_min_f32_e32 v20, 0x3f7fffef, v20
	v_min_f32_e32 v21, 0x3f7fffef, v21
	v_min_f32_e32 v22, 0x3f7fffef, v22
	v_min_f32_e32 v23, 0x3f7fffef, v23
	v_min_f32_e32 v24, 0x3f7fffef, v24
	v_min_f32_e32 v25, 0x3f7fffef, v25
	v_pk_add_f32 v[18:19], v[18:19], 1.0 op_sel_hi:[1,0] neg_lo:[1,0] neg_hi:[1,0]
	v_pk_add_f32 v[20:21], v[20:21], 1.0 op_sel_hi:[1,0] neg_lo:[1,0] neg_hi:[1,0]
	v_pk_add_f32 v[22:23], v[22:23], 1.0 op_sel_hi:[1,0] neg_lo:[1,0] neg_hi:[1,0]
	v_pk_add_f32 v[24:25], v[24:25], 1.0 op_sel_hi:[1,0] neg_lo:[1,0] neg_hi:[1,0]
	v_log_f32_e32 v18, v18
	v_log_f32_e32 v19, v19
	v_log_f32_e32 v20, v20
	v_log_f32_e32 v21, v21
	v_log_f32_e32 v22, v22
	v_log_f32_e32 v23, v23
	v_log_f32_e32 v24, v24
	v_log_f32_e32 v25, v25
	v_pk_mul_f32 v[244:245], v[18:19], s[76:77] op_sel_hi:[1,0]
	v_pk_fma_f32 v[244:245], v[18:19], s[76:77], v[244:245] op_sel_hi:[1,0,1] neg_lo:[0,0,1] neg_hi:[0,0,1]
	v_pk_fma_f32 v[244:245], v[18:19], s[12:13], v[244:245] op_sel_hi:[1,0,1]
	v_pk_fma_f32 v[18:19], v[18:19], s[76:77], v[244:245] op_sel_hi:[1,0,1]
	v_pk_mul_f32 v[246:247], v[20:21], s[76:77] op_sel_hi:[1,0]
	v_pk_fma_f32 v[246:247], v[20:21], s[76:77], v[246:247] op_sel_hi:[1,0,1] neg_lo:[0,0,1] neg_hi:[0,0,1]
	v_pk_fma_f32 v[246:247], v[20:21], s[12:13], v[246:247] op_sel_hi:[1,0,1]
	v_pk_fma_f32 v[20:21], v[20:21], s[76:77], v[246:247] op_sel_hi:[1,0,1]
	v_pk_mul_f32 v[244:245], v[22:23], s[76:77] op_sel_hi:[1,0]
	v_pk_fma_f32 v[244:245], v[22:23], s[76:77], v[244:245] op_sel_hi:[1,0,1] neg_lo:[0,0,1] neg_hi:[0,0,1]
	v_pk_fma_f32 v[244:245], v[22:23], s[12:13], v[244:245] op_sel_hi:[1,0,1]
	v_pk_fma_f32 v[22:23], v[22:23], s[76:77], v[244:245] op_sel_hi:[1,0,1]
	v_pk_mul_f32 v[246:247], v[24:25], s[76:77] op_sel_hi:[1,0]
	v_pk_fma_f32 v[246:247], v[24:25], s[76:77], v[246:247] op_sel_hi:[1,0,1] neg_lo:[0,0,1] neg_hi:[0,0,1]
	v_pk_fma_f32 v[246:247], v[24:25], s[12:13], v[246:247] op_sel_hi:[1,0,1]
	v_pk_fma_f32 v[24:25], v[24:25], s[76:77], v[246:247] op_sel_hi:[1,0,1]
	s_mov_b64 s[4:5], 0
	global_store_dwordx4 v[36:37], v[18:21], off
	global_store_dwordx4 v[36:37], v[22:25], off offset:16

.LBB0_949:
	s_andn2_b64 vcc, exec, s[0:1]
	s_cbranch_vccnz .LBB0_794
	v_mad_i64_i32 v[28:29], s[0:1], v18, s33, v[122:123]
	s_cmp_gt_i32 s71, 8
	s_mov_b64 s[0:1], -1
	s_cbranch_scc1 .LBB0_956
	s_cmp_lt_u32 s73, 5
	s_cselect_b64 s[0:1], -1, 0
	s_cmp_gt_u32 s73, 4
	s_cbranch_scc0 .LBB0_956
	s_andn2_b64 vcc, exec, s[28:29]
	s_mov_b64 s[4:5], -1
	s_cbranch_vccnz .LBB0_954
	s_mov_b32 s4, 0x3fb8aa3b
	s_mov_b32 s12, 0x3f317217
	s_mov_b32 s10, 0x3377d1cf
	v_lshl_add_u64 v[30:31], v[28:29], 2, s[86:87]
	v_pk_mul_f32 v[2:3], v[26:27], s[4:5] op_sel_hi:[1,0]
	v_pk_mul_f32 v[4:5], v[24:25], s[4:5] op_sel_hi:[1,0]
	v_pk_mul_f32 v[6:7], v[22:23], s[4:5] op_sel_hi:[1,0]
	v_pk_mul_f32 v[8:9], v[20:21], s[4:5] op_sel_hi:[1,0]
	v_exp_f32_e32 v2, v2
	v_exp_f32_e32 v3, v3
	v_exp_f32_e32 v4, v4
	v_exp_f32_e32 v5, v5
	v_exp_f32_e32 v6, v6
	v_exp_f32_e32 v7, v7
	v_exp_f32_e32 v8, v8
	v_exp_f32_e32 v9, v9
	v_pk_add_f32 v[2:3], v[2:3], 1.0 op_sel_hi:[1,0]
	v_pk_add_f32 v[4:5], v[4:5], 1.0 op_sel_hi:[1,0]
	v_pk_add_f32 v[6:7], v[6:7], 1.0 op_sel_hi:[1,0]
	v_pk_add_f32 v[8:9], v[8:9], 1.0 op_sel_hi:[1,0]
	v_rcp_f32_e32 v2, v2
	v_rcp_f32_e32 v3, v3
	v_rcp_f32_e32 v4, v4
	v_rcp_f32_e32 v5, v5
	v_rcp_f32_e32 v6, v6
	v_rcp_f32_e32 v7, v7
	v_rcp_f32_e32 v8, v8
	v_rcp_f32_e32 v9, v9
	v_pk_mul_f32 v[2:3], v[2:3], v[220:221]
	v_pk_mul_f32 v[4:5], v[4:5], v[222:223]
	v_pk_mul_f32 v[6:7], v[6:7], v[224:225]
	v_pk_mul_f32 v[8:9], v[8:9], v[226:227]
	v_min_f32_e32 v2, 0x3f7fffef, v2
	v_min_f32_e32 v3, 0x3f7fffef, v3
	v_min_f32_e32 v4, 0x3f7fffef, v4
	v_min_f32_e32 v5, 0x3f7fffef, v5
	v_min_f32_e32 v6, 0x3f7fffef, v6
	v_min_f32_e32 v7, 0x3f7fffef, v7
	v_min_f32_e32 v8, 0x3f7fffef, v8
	v_min_f32_e32 v9, 0x3f7fffef, v9
	v_pk_add_f32 v[2:3], v[2:3], 1.0 op_sel_hi:[1,0] neg_lo:[1,0] neg_hi:[1,0]
	v_pk_add_f32 v[4:5], v[4:5], 1.0 op_sel_hi:[1,0] neg_lo:[1,0] neg_hi:[1,0]
	v_pk_add_f32 v[6:7], v[6:7], 1.0 op_sel_hi:[1,0] neg_lo:[1,0] neg_hi:[1,0]
	v_pk_add_f32 v[8:9], v[8:9], 1.0 op_sel_hi:[1,0] neg_lo:[1,0] neg_hi:[1,0]
	v_log_f32_e32 v2, v2
	v_log_f32_e32 v3, v3
	v_log_f32_e32 v4, v4
	v_log_f32_e32 v5, v5
	v_log_f32_e32 v6, v6
	v_log_f32_e32 v7, v7
	v_log_f32_e32 v8, v8
	v_log_f32_e32 v9, v9
	v_pk_mul_f32 v[244:245], v[2:3], s[12:13] op_sel_hi:[1,0]
	v_pk_fma_f32 v[244:245], v[2:3], s[12:13], v[244:245] op_sel_hi:[1,0,1] neg_lo:[0,0,1] neg_hi:[0,0,1]
	v_pk_fma_f32 v[244:245], v[2:3], s[10:11], v[244:245] op_sel_hi:[1,0,1]
	v_pk_fma_f32 v[2:3], v[2:3], s[12:13], v[244:245] op_sel_hi:[1,0,1]
	v_pk_mul_f32 v[246:247], v[4:5], s[12:13] op_sel_hi:[1,0]
	v_pk_fma_f32 v[246:247], v[4:5], s[12:13], v[246:247] op_sel_hi:[1,0,1] neg_lo:[0,0,1] neg_hi:[0,0,1]
	v_pk_fma_f32 v[246:247], v[4:5], s[10:11], v[246:247] op_sel_hi:[1,0,1]
	v_pk_fma_f32 v[4:5], v[4:5], s[12:13], v[246:247] op_sel_hi:[1,0,1]
	v_pk_mul_f32 v[244:245], v[6:7], s[12:13] op_sel_hi:[1,0]
	v_pk_fma_f32 v[244:245], v[6:7], s[12:13], v[244:245] op_sel_hi:[1,0,1] neg_lo:[0,0,1] neg_hi:[0,0,1]
	v_pk_fma_f32 v[244:245], v[6:7], s[10:11], v[244:245] op_sel_hi:[1,0,1]
	v_pk_fma_f32 v[6:7], v[6:7], s[12:13], v[244:245] op_sel_hi:[1,0,1]
	v_pk_mul_f32 v[246:247], v[8:9], s[12:13] op_sel_hi:[1,0]
	v_pk_fma_f32 v[246:247], v[8:9], s[12:13], v[246:247] op_sel_hi:[1,0,1] neg_lo:[0,0,1] neg_hi:[0,0,1]
	v_pk_fma_f32 v[246:247], v[8:9], s[10:11], v[246:247] op_sel_hi:[1,0,1]
	v_pk_fma_f32 v[8:9], v[8:9], s[12:13], v[246:247] op_sel_hi:[1,0,1]
	s_mov_b64 s[4:5], 0
	global_store_dwordx4 v[30:31], v[2:5], off
	global_store_dwordx4 v[30:31], v[6:9], off offset:16

.LBB0_958:
	s_nop 1
	v_mad_i64_i32 v[2:3], s[0:1], v18, s33, 0
	v_lshl_add_u64 v[18:19], v[2:3], 0, v[124:125]
	s_cmp_gt_i32 s71, 8
	s_mov_b64 s[0:1], -1
	s_cbranch_scc1 .LBB0_964
	s_cmp_lt_u32 s73, 5
	s_cselect_b64 s[0:1], -1, 0
	s_cmp_gt_u32 s73, 4
	s_cbranch_scc0 .LBB0_964
	s_andn2_b64 vcc, exec, s[28:29]
	s_mov_b64 s[4:5], -1
	s_cbranch_vccnz .LBB0_962
	s_mov_b32 s4, 0x3fb8aa3b
	s_mov_b32 s12, 0x3f317217
	s_mov_b32 s10, 0x3377d1cf
	v_lshl_add_u64 v[20:21], v[18:19], 2, s[86:87]
	v_pk_mul_f32 v[2:3], v[16:17], s[4:5] op_sel_hi:[1,0]
	v_pk_mul_f32 v[4:5], v[14:15], s[4:5] op_sel_hi:[1,0]
	v_pk_mul_f32 v[6:7], v[12:13], s[4:5] op_sel_hi:[1,0]
	v_pk_mul_f32 v[8:9], v[10:11], s[4:5] op_sel_hi:[1,0]
	v_exp_f32_e32 v2, v2
	v_exp_f32_e32 v3, v3
	v_exp_f32_e32 v4, v4
	v_exp_f32_e32 v5, v5
	v_exp_f32_e32 v6, v6
	v_exp_f32_e32 v7, v7
	v_exp_f32_e32 v8, v8
	v_exp_f32_e32 v9, v9
	v_pk_add_f32 v[2:3], v[2:3], 1.0 op_sel_hi:[1,0]
	v_pk_add_f32 v[4:5], v[4:5], 1.0 op_sel_hi:[1,0]
	v_pk_add_f32 v[6:7], v[6:7], 1.0 op_sel_hi:[1,0]
	v_pk_add_f32 v[8:9], v[8:9], 1.0 op_sel_hi:[1,0]
	v_rcp_f32_e32 v2, v2
	v_rcp_f32_e32 v3, v3
	v_rcp_f32_e32 v4, v4
	v_rcp_f32_e32 v5, v5
	v_rcp_f32_e32 v6, v6
	v_rcp_f32_e32 v7, v7
	v_rcp_f32_e32 v8, v8
	v_rcp_f32_e32 v9, v9
	v_pk_mul_f32 v[2:3], v[2:3], v[228:229]
	v_pk_mul_f32 v[4:5], v[4:5], v[230:231]
	v_pk_mul_f32 v[6:7], v[6:7], v[232:233]
	v_pk_mul_f32 v[8:9], v[8:9], v[234:235]
	v_min_f32_e32 v2, 0x3f7fffef, v2
	v_min_f32_e32 v3, 0x3f7fffef, v3
	v_min_f32_e32 v4, 0x3f7fffef, v4
	v_min_f32_e32 v5, 0x3f7fffef, v5
	v_min_f32_e32 v6, 0x3f7fffef, v6
	v_min_f32_e32 v7, 0x3f7fffef, v7
	v_min_f32_e32 v8, 0x3f7fffef, v8
	v_min_f32_e32 v9, 0x3f7fffef, v9
	v_pk_add_f32 v[2:3], v[2:3], 1.0 op_sel_hi:[1,0] neg_lo:[1,0] neg_hi:[1,0]
	v_pk_add_f32 v[4:5], v[4:5], 1.0 op_sel_hi:[1,0] neg_lo:[1,0] neg_hi:[1,0]
	v_pk_add_f32 v[6:7], v[6:7], 1.0 op_sel_hi:[1,0] neg_lo:[1,0] neg_hi:[1,0]
	v_pk_add_f32 v[8:9], v[8:9], 1.0 op_sel_hi:[1,0] neg_lo:[1,0] neg_hi:[1,0]
	v_log_f32_e32 v2, v2
	v_log_f32_e32 v3, v3
	v_log_f32_e32 v4, v4
	v_log_f32_e32 v5, v5
	v_log_f32_e32 v6, v6
	v_log_f32_e32 v7, v7
	v_log_f32_e32 v8, v8
	v_log_f32_e32 v9, v9
	v_pk_mul_f32 v[244:245], v[2:3], s[12:13] op_sel_hi:[1,0]
	v_pk_fma_f32 v[244:245], v[2:3], s[12:13], v[244:245] op_sel_hi:[1,0,1] neg_lo:[0,0,1] neg_hi:[0,0,1]
	v_pk_fma_f32 v[244:245], v[2:3], s[10:11], v[244:245] op_sel_hi:[1,0,1]
	v_pk_fma_f32 v[2:3], v[2:3], s[12:13], v[244:245] op_sel_hi:[1,0,1]
	v_pk_mul_f32 v[246:247], v[4:5], s[12:13] op_sel_hi:[1,0]
	v_pk_fma_f32 v[246:247], v[4:5], s[12:13], v[246:247] op_sel_hi:[1,0,1] neg_lo:[0,0,1] neg_hi:[0,0,1]
	v_pk_fma_f32 v[246:247], v[4:5], s[10:11], v[246:247] op_sel_hi:[1,0,1]
	v_pk_fma_f32 v[4:5], v[4:5], s[12:13], v[246:247] op_sel_hi:[1,0,1]
	v_pk_mul_f32 v[244:245], v[6:7], s[12:13] op_sel_hi:[1,0]
	v_pk_fma_f32 v[244:245], v[6:7], s[12:13], v[244:245] op_sel_hi:[1,0,1] neg_lo:[0,0,1] neg_hi:[0,0,1]
	v_pk_fma_f32 v[244:245], v[6:7], s[10:11], v[244:245] op_sel_hi:[1,0,1]
	v_pk_fma_f32 v[6:7], v[6:7], s[12:13], v[244:245] op_sel_hi:[1,0,1]
	v_pk_mul_f32 v[246:247], v[8:9], s[12:13] op_sel_hi:[1,0]
	v_pk_fma_f32 v[246:247], v[8:9], s[12:13], v[246:247] op_sel_hi:[1,0,1] neg_lo:[0,0,1] neg_hi:[0,0,1]
	v_pk_fma_f32 v[246:247], v[8:9], s[10:11], v[246:247] op_sel_hi:[1,0,1]
	v_pk_fma_f32 v[8:9], v[8:9], s[12:13], v[246:247] op_sel_hi:[1,0,1]
	s_mov_b64 s[4:5], 0
	global_store_dwordx4 v[20:21], v[2:5], off
	global_store_dwordx4 v[20:21], v[6:9], off offset:16

.LBB0_966:
	s_andn2_b64 vcc, exec, s[28:29]
	s_mov_b64 s[0:1], -1
	s_cbranch_vccnz .LBB0_968
	s_mov_b32 s0, 0x3fb8aa3b
	s_mov_b32 s4, 0x3f317217
	s_mov_b32 s10, 0x3377d1cf
	v_lshl_add_u64 v[160:161], v[158:159], 2, s[86:87]
	v_pk_mul_f32 v[114:115], v[156:157], s[0:1] op_sel_hi:[1,0]
	v_pk_mul_f32 v[116:117], v[154:155], s[0:1] op_sel_hi:[1,0]
	v_pk_mul_f32 v[118:119], v[152:153], s[0:1] op_sel_hi:[1,0]
	v_pk_mul_f32 v[120:121], v[150:151], s[0:1] op_sel_hi:[1,0]
	v_exp_f32_e32 v114, v114
	v_exp_f32_e32 v115, v115
	v_exp_f32_e32 v116, v116
	v_exp_f32_e32 v117, v117
	v_exp_f32_e32 v118, v118
	v_exp_f32_e32 v119, v119
	v_exp_f32_e32 v120, v120
	v_exp_f32_e32 v121, v121
	v_pk_add_f32 v[114:115], v[114:115], 1.0 op_sel_hi:[1,0]
	v_pk_add_f32 v[116:117], v[116:117], 1.0 op_sel_hi:[1,0]
	v_pk_add_f32 v[118:119], v[118:119], 1.0 op_sel_hi:[1,0]
	v_pk_add_f32 v[120:121], v[120:121], 1.0 op_sel_hi:[1,0]
	v_rcp_f32_e32 v114, v114
	v_rcp_f32_e32 v115, v115
	v_rcp_f32_e32 v116, v116
	v_rcp_f32_e32 v117, v117
	v_rcp_f32_e32 v118, v118
	v_rcp_f32_e32 v119, v119
	v_rcp_f32_e32 v120, v120
	v_rcp_f32_e32 v121, v121
	v_pk_mul_f32 v[114:115], v[114:115], v[228:229]
	v_pk_mul_f32 v[116:117], v[116:117], v[230:231]
	v_pk_mul_f32 v[118:119], v[118:119], v[232:233]
	v_pk_mul_f32 v[120:121], v[120:121], v[234:235]
	v_min_f32_e32 v114, 0x3f7fffef, v114
	v_min_f32_e32 v115, 0x3f7fffef, v115
	v_min_f32_e32 v116, 0x3f7fffef, v116
	v_min_f32_e32 v117, 0x3f7fffef, v117
	v_min_f32_e32 v118, 0x3f7fffef, v118
	v_min_f32_e32 v119, 0x3f7fffef, v119
	v_min_f32_e32 v120, 0x3f7fffef, v120
	v_min_f32_e32 v121, 0x3f7fffef, v121
	v_pk_add_f32 v[114:115], v[114:115], 1.0 op_sel_hi:[1,0] neg_lo:[1,0] neg_hi:[1,0]
	v_pk_add_f32 v[116:117], v[116:117], 1.0 op_sel_hi:[1,0] neg_lo:[1,0] neg_hi:[1,0]
	v_pk_add_f32 v[118:119], v[118:119], 1.0 op_sel_hi:[1,0] neg_lo:[1,0] neg_hi:[1,0]
	v_pk_add_f32 v[120:121], v[120:121], 1.0 op_sel_hi:[1,0] neg_lo:[1,0] neg_hi:[1,0]
	v_log_f32_e32 v114, v114
	v_log_f32_e32 v115, v115
	v_log_f32_e32 v116, v116
	v_log_f32_e32 v117, v117
	v_log_f32_e32 v118, v118
	v_log_f32_e32 v119, v119
	v_log_f32_e32 v120, v120
	v_log_f32_e32 v121, v121
	v_pk_mul_f32 v[244:245], v[114:115], s[4:5] op_sel_hi:[1,0]
	v_pk_fma_f32 v[244:245], v[114:115], s[4:5], v[244:245] op_sel_hi:[1,0,1] neg_lo:[0,0,1] neg_hi:[0,0,1]
	v_pk_fma_f32 v[244:245], v[114:115], s[10:11], v[244:245] op_sel_hi:[1,0,1]
	v_pk_fma_f32 v[114:115], v[114:115], s[4:5], v[244:245] op_sel_hi:[1,0,1]
	v_pk_mul_f32 v[246:247], v[116:117], s[4:5] op_sel_hi:[1,0]
	v_pk_fma_f32 v[246:247], v[116:117], s[4:5], v[246:247] op_sel_hi:[1,0,1] neg_lo:[0,0,1] neg_hi:[0,0,1]
	v_pk_fma_f32 v[246:247], v[116:117], s[10:11], v[246:247] op_sel_hi:[1,0,1]
	v_pk_fma_f32 v[116:117], v[116:117], s[4:5], v[246:247] op_sel_hi:[1,0,1]
	v_pk_mul_f32 v[244:245], v[118:119], s[4:5] op_sel_hi:[1,0]
	v_pk_fma_f32 v[244:245], v[118:119], s[4:5], v[244:245] op_sel_hi:[1,0,1] neg_lo:[0,0,1] neg_hi:[0,0,1]
	v_pk_fma_f32 v[244:245], v[118:119], s[10:11], v[244:245] op_sel_hi:[1,0,1]
	v_pk_fma_f32 v[118:119], v[118:119], s[4:5], v[244:245] op_sel_hi:[1,0,1]
	v_pk_mul_f32 v[246:247], v[120:121], s[4:5] op_sel_hi:[1,0]
	v_pk_fma_f32 v[246:247], v[120:121], s[4:5], v[246:247] op_sel_hi:[1,0,1] neg_lo:[0,0,1] neg_hi:[0,0,1]
	v_pk_fma_f32 v[246:247], v[120:121], s[10:11], v[246:247] op_sel_hi:[1,0,1]
	v_pk_fma_f32 v[120:121], v[120:121], s[4:5], v[246:247] op_sel_hi:[1,0,1]
	s_mov_b64 s[0:1], 0
	global_store_dwordx4 v[160:161], v[114:117], off
	global_store_dwordx4 v[160:161], v[118:121], off offset:16

	.amdhsa_kernel _Z8yoco_fwd6Params
		.amdhsa_group_segment_fixed_size 0
		.amdhsa_private_segment_fixed_size 0
		.amdhsa_kernarg_size 1336
		.amdhsa_user_sgpr_count 2
		.amdhsa_user_sgpr_dispatch_ptr 0
		.amdhsa_user_sgpr_queue_ptr 0
		.amdhsa_user_sgpr_kernarg_segment_ptr 1
		.amdhsa_user_sgpr_dispatch_id 0
		.amdhsa_user_sgpr_kernarg_preload_length 0
		.amdhsa_user_sgpr_kernarg_preload_offset 0
		.amdhsa_user_sgpr_private_segment_size 0
		.amdhsa_uses_dynamic_stack 0
		.amdhsa_enable_private_segment 0
		.amdhsa_system_sgpr_workgroup_id_x 1
		.amdhsa_system_sgpr_workgroup_id_y 0
		.amdhsa_system_sgpr_workgroup_id_z 0
		.amdhsa_system_sgpr_workgroup_info 0
		.amdhsa_system_vgpr_workitem_id 2
		.amdhsa_next_free_vgpr 248
		.amdhsa_next_free_sgpr 100
		.amdhsa_accum_offset 248
		.amdhsa_reserve_vcc 1
		.amdhsa_float_round_mode_32 0
		.amdhsa_float_round_mode_16_64 0
		.amdhsa_float_denorm_mode_32 3
		.amdhsa_float_denorm_mode_16_64 3
		.amdhsa_dx10_clamp 1
		.amdhsa_ieee_mode 1
		.amdhsa_fp16_overflow 0
		.amdhsa_tg_split 0
		.amdhsa_exception_fp_ieee_invalid_op 0
		.amdhsa_exception_fp_denorm_src 0
		.amdhsa_exception_fp_ieee_div_zero 0
		.amdhsa_exception_fp_ieee_overflow 0
		.amdhsa_exception_fp_ieee_underflow 0
		.amdhsa_exception_fp_ieee_inexact 0
		.amdhsa_exception_int_div_zero 0
	.end_amdhsa_kernel

amdhsa.kernels:
  - .agpr_count:     0
    .args:
      - .offset:         0
        .size:           1080
        .value_kind:     by_value
      - .offset:         1080
        .size:           4
        .value_kind:     hidden_block_count_x
      - .offset:         1084
        .size:           4
        .value_kind:     hidden_block_count_y
      - .offset:         1088
        .size:           4
        .value_kind:     hidden_block_count_z
      - .offset:         1092
        .size:           2
        .value_kind:     hidden_group_size_x
      - .offset:         1094
        .size:           2
        .value_kind:     hidden_group_size_y
      - .offset:         1096
        .size:           2
        .value_kind:     hidden_group_size_z
      - .offset:         1098
        .size:           2
        .value_kind:     hidden_remainder_x
      - .offset:         1100
        .size:           2
        .value_kind:     hidden_remainder_y
      - .offset:         1102
        .size:           2
        .value_kind:     hidden_remainder_z
      - .offset:         1120
        .size:           8
        .value_kind:     hidden_global_offset_x
      - .offset:         1128
        .size:           8
        .value_kind:     hidden_global_offset_y
      - .offset:         1136
        .size:           8
        .value_kind:     hidden_global_offset_z
      - .offset:         1144
        .size:           2
        .value_kind:     hidden_grid_dims
      - .offset:         1168
        .size:           8
        .value_kind:     hidden_multigrid_sync_arg
      - .offset:         1200
        .size:           4
        .value_kind:     hidden_dynamic_lds_size
    .group_segment_fixed_size: 0
    .kernarg_segment_align: 8
    .kernarg_segment_size: 1336
    .language:       OpenCL C
    .language_version:
      - 2
      - 0
    .max_flat_workgroup_size: 512
    .name:           _Z8yoco_fwd6Params
    .private_segment_fixed_size: 0
    .sgpr_count:     106
    .sgpr_spill_count: 229
    .symbol:         _Z8yoco_fwd6Params.kd
    .uniform_work_group_size: 1
    .uses_dynamic_stack: false
    .vgpr_count:     248
    .vgpr_spill_count: 0
    .wavefront_size: 64
